# INA: f32 log-gate result stores marked nt (streaming), other INA stores unchanged
# speedup vs baseline: 1.0275x; 1.0007x over previous
.LBB0_822:
	s_mov_b64 s[0:1], -1
	s_and_b64 vcc, exec, s[28:29]
	s_cbranch_vccz .LBB0_824
	s_mov_b32 s0, 0x3fb8aa3b
	s_mov_b32 s4, 0x3f317217
	s_mov_b32 s10, 0x3377d1cf
	v_lshl_add_u64 v[176:177], v[168:169], 2, s[86:87]
	v_pk_mul_f32 v[114:115], v[166:167], s[0:1] op_sel_hi:[1,0]
	v_pk_mul_f32 v[116:117], v[164:165], s[0:1] op_sel_hi:[1,0]
	v_pk_mul_f32 v[118:119], v[162:163], s[0:1] op_sel_hi:[1,0]
	v_pk_mul_f32 v[120:121], v[160:161], s[0:1] op_sel_hi:[1,0]
	v_exp_f32_e32 v114, v114
	v_exp_f32_e32 v115, v115
	v_exp_f32_e32 v116, v116
	v_exp_f32_e32 v117, v117
	v_exp_f32_e32 v118, v118
	v_exp_f32_e32 v119, v119
	v_exp_f32_e32 v120, v120
	v_exp_f32_e32 v121, v121
	v_pk_add_f32 v[114:115], v[114:115], 1.0 op_sel_hi:[1,0]
	v_pk_add_f32 v[116:117], v[116:117], 1.0 op_sel_hi:[1,0]
	v_pk_add_f32 v[118:119], v[118:119], 1.0 op_sel_hi:[1,0]
	v_pk_add_f32 v[120:121], v[120:121], 1.0 op_sel_hi:[1,0]
	v_rcp_f32_e32 v114, v114
	v_rcp_f32_e32 v115, v115
	v_rcp_f32_e32 v116, v116
	v_rcp_f32_e32 v117, v117
	v_rcp_f32_e32 v118, v118
	v_rcp_f32_e32 v119, v119
	v_rcp_f32_e32 v120, v120
	v_rcp_f32_e32 v121, v121
	s_waitcnt vmcnt(0)
	v_pk_mul_f32 v[114:115], v[114:115], v[220:221]
	v_pk_mul_f32 v[116:117], v[116:117], v[222:223]
	v_pk_mul_f32 v[118:119], v[118:119], v[224:225]
	v_pk_mul_f32 v[120:121], v[120:121], v[226:227]
	v_min_f32_e32 v114, 0x3f7fffef, v114
	v_min_f32_e32 v115, 0x3f7fffef, v115
	v_min_f32_e32 v116, 0x3f7fffef, v116
	v_min_f32_e32 v117, 0x3f7fffef, v117
	v_min_f32_e32 v118, 0x3f7fffef, v118
	v_min_f32_e32 v119, 0x3f7fffef, v119
	v_min_f32_e32 v120, 0x3f7fffef, v120
	v_min_f32_e32 v121, 0x3f7fffef, v121
	v_pk_add_f32 v[114:115], v[114:115], 1.0 op_sel_hi:[1,0] neg_lo:[1,0] neg_hi:[1,0]
	v_pk_add_f32 v[116:117], v[116:117], 1.0 op_sel_hi:[1,0] neg_lo:[1,0] neg_hi:[1,0]
	v_pk_add_f32 v[118:119], v[118:119], 1.0 op_sel_hi:[1,0] neg_lo:[1,0] neg_hi:[1,0]
	v_pk_add_f32 v[120:121], v[120:121], 1.0 op_sel_hi:[1,0] neg_lo:[1,0] neg_hi:[1,0]
	v_log_f32_e32 v114, v114
	v_log_f32_e32 v115, v115
	v_log_f32_e32 v116, v116
	v_log_f32_e32 v117, v117
	v_log_f32_e32 v118, v118
	v_log_f32_e32 v119, v119
	v_log_f32_e32 v120, v120
	v_log_f32_e32 v121, v121
	v_pk_mul_f32 v[244:245], v[114:115], s[4:5] op_sel_hi:[1,0]
	v_pk_fma_f32 v[244:245], v[114:115], s[4:5], v[244:245] op_sel_hi:[1,0,1] neg_lo:[0,0,1] neg_hi:[0,0,1]
	v_pk_fma_f32 v[244:245], v[114:115], s[10:11], v[244:245] op_sel_hi:[1,0,1]
	v_pk_fma_f32 v[114:115], v[114:115], s[4:5], v[244:245] op_sel_hi:[1,0,1]
	v_pk_mul_f32 v[246:247], v[116:117], s[4:5] op_sel_hi:[1,0]
	v_pk_fma_f32 v[246:247], v[116:117], s[4:5], v[246:247] op_sel_hi:[1,0,1] neg_lo:[0,0,1] neg_hi:[0,0,1]
	v_pk_fma_f32 v[246:247], v[116:117], s[10:11], v[246:247] op_sel_hi:[1,0,1]
	v_pk_fma_f32 v[116:117], v[116:117], s[4:5], v[246:247] op_sel_hi:[1,0,1]
	v_pk_mul_f32 v[244:245], v[118:119], s[4:5] op_sel_hi:[1,0]
	v_pk_fma_f32 v[244:245], v[118:119], s[4:5], v[244:245] op_sel_hi:[1,0,1] neg_lo:[0,0,1] neg_hi:[0,0,1]
	v_pk_fma_f32 v[244:245], v[118:119], s[10:11], v[244:245] op_sel_hi:[1,0,1]
	v_pk_fma_f32 v[118:119], v[118:119], s[4:5], v[244:245] op_sel_hi:[1,0,1]
	v_pk_mul_f32 v[246:247], v[120:121], s[4:5] op_sel_hi:[1,0]
	v_pk_fma_f32 v[246:247], v[120:121], s[4:5], v[246:247] op_sel_hi:[1,0,1] neg_lo:[0,0,1] neg_hi:[0,0,1]
	v_pk_fma_f32 v[246:247], v[120:121], s[10:11], v[246:247] op_sel_hi:[1,0,1]
	v_pk_fma_f32 v[120:121], v[120:121], s[4:5], v[246:247] op_sel_hi:[1,0,1]
	s_mov_b64 s[0:1], 0
	global_store_dwordx4 v[176:177], v[114:117], off nt
	global_store_dwordx4 v[176:177], v[118:121], off offset:16 nt

.LBB0_835:
	s_andn2_b64 vcc, exec, s[0:1]
	s_cbranch_vccnz .LBB0_852
	v_mad_i64_i32 v[150:151], s[0:1], v114, s33, v[122:123]
	s_cmp_gt_i32 s71, 8
	s_mov_b64 s[0:1], -1
	s_cbranch_scc1 .LBB0_842
	s_cmp_lt_u32 s73, 5
	s_cselect_b64 s[0:1], -1, 0
	s_cmp_gt_u32 s73, 4
	s_cbranch_scc0 .LBB0_842
	s_andn2_b64 vcc, exec, s[28:29]
	s_mov_b64 s[4:5], -1
	s_cbranch_vccnz .LBB0_840
	s_mov_b32 s4, 0x3fb8aa3b
	s_mov_b32 s76, 0x3f317217
	s_mov_b32 s12, 0x3377d1cf
	v_lshl_add_u64 v[152:153], v[150:151], 2, s[86:87]
	v_pk_mul_f32 v[98:99], v[148:149], s[4:5] op_sel_hi:[1,0]
	v_pk_mul_f32 v[100:101], v[120:121], s[4:5] op_sel_hi:[1,0]
	v_pk_mul_f32 v[102:103], v[118:119], s[4:5] op_sel_hi:[1,0]
	v_pk_mul_f32 v[104:105], v[116:117], s[4:5] op_sel_hi:[1,0]
	v_exp_f32_e32 v98, v98
	v_exp_f32_e32 v99, v99
	v_exp_f32_e32 v100, v100
	v_exp_f32_e32 v101, v101
	v_exp_f32_e32 v102, v102
	v_exp_f32_e32 v103, v103
	v_exp_f32_e32 v104, v104
	v_exp_f32_e32 v105, v105
	v_pk_add_f32 v[98:99], v[98:99], 1.0 op_sel_hi:[1,0]
	v_pk_add_f32 v[100:101], v[100:101], 1.0 op_sel_hi:[1,0]
	v_pk_add_f32 v[102:103], v[102:103], 1.0 op_sel_hi:[1,0]
	v_pk_add_f32 v[104:105], v[104:105], 1.0 op_sel_hi:[1,0]
	v_rcp_f32_e32 v98, v98
	v_rcp_f32_e32 v99, v99
	v_rcp_f32_e32 v100, v100
	v_rcp_f32_e32 v101, v101
	v_rcp_f32_e32 v102, v102
	v_rcp_f32_e32 v103, v103
	v_rcp_f32_e32 v104, v104
	v_rcp_f32_e32 v105, v105
	v_pk_mul_f32 v[98:99], v[98:99], v[220:221]
	v_pk_mul_f32 v[100:101], v[100:101], v[222:223]
	v_pk_mul_f32 v[102:103], v[102:103], v[224:225]
	v_pk_mul_f32 v[104:105], v[104:105], v[226:227]
	v_min_f32_e32 v98, 0x3f7fffef, v98
	v_min_f32_e32 v99, 0x3f7fffef, v99
	v_min_f32_e32 v100, 0x3f7fffef, v100
	v_min_f32_e32 v101, 0x3f7fffef, v101
	v_min_f32_e32 v102, 0x3f7fffef, v102
	v_min_f32_e32 v103, 0x3f7fffef, v103
	v_min_f32_e32 v104, 0x3f7fffef, v104
	v_min_f32_e32 v105, 0x3f7fffef, v105
	v_pk_add_f32 v[98:99], v[98:99], 1.0 op_sel_hi:[1,0] neg_lo:[1,0] neg_hi:[1,0]
	v_pk_add_f32 v[100:101], v[100:101], 1.0 op_sel_hi:[1,0] neg_lo:[1,0] neg_hi:[1,0]
	v_pk_add_f32 v[102:103], v[102:103], 1.0 op_sel_hi:[1,0] neg_lo:[1,0] neg_hi:[1,0]
	v_pk_add_f32 v[104:105], v[104:105], 1.0 op_sel_hi:[1,0] neg_lo:[1,0] neg_hi:[1,0]
	v_log_f32_e32 v98, v98
	v_log_f32_e32 v99, v99
	v_log_f32_e32 v100, v100
	v_log_f32_e32 v101, v101
	v_log_f32_e32 v102, v102
	v_log_f32_e32 v103, v103
	v_log_f32_e32 v104, v104
	v_log_f32_e32 v105, v105
	v_pk_mul_f32 v[244:245], v[98:99], s[76:77] op_sel_hi:[1,0]
	v_pk_fma_f32 v[244:245], v[98:99], s[76:77], v[244:245] op_sel_hi:[1,0,1] neg_lo:[0,0,1] neg_hi:[0,0,1]
	v_pk_fma_f32 v[244:245], v[98:99], s[12:13], v[244:245] op_sel_hi:[1,0,1]
	v_pk_fma_f32 v[98:99], v[98:99], s[76:77], v[244:245] op_sel_hi:[1,0,1]
	v_pk_mul_f32 v[246:247], v[100:101], s[76:77] op_sel_hi:[1,0]
	v_pk_fma_f32 v[246:247], v[100:101], s[76:77], v[246:247] op_sel_hi:[1,0,1] neg_lo:[0,0,1] neg_hi:[0,0,1]
	v_pk_fma_f32 v[246:247], v[100:101], s[12:13], v[246:247] op_sel_hi:[1,0,1]
	v_pk_fma_f32 v[100:101], v[100:101], s[76:77], v[246:247] op_sel_hi:[1,0,1]
	v_pk_mul_f32 v[244:245], v[102:103], s[76:77] op_sel_hi:[1,0]
	v_pk_fma_f32 v[244:245], v[102:103], s[76:77], v[244:245] op_sel_hi:[1,0,1] neg_lo:[0,0,1] neg_hi:[0,0,1]
	v_pk_fma_f32 v[244:245], v[102:103], s[12:13], v[244:245] op_sel_hi:[1,0,1]
	v_pk_fma_f32 v[102:103], v[102:103], s[76:77], v[244:245] op_sel_hi:[1,0,1]
	v_pk_mul_f32 v[246:247], v[104:105], s[76:77] op_sel_hi:[1,0]
	v_pk_fma_f32 v[246:247], v[104:105], s[76:77], v[246:247] op_sel_hi:[1,0,1] neg_lo:[0,0,1] neg_hi:[0,0,1]
	v_pk_fma_f32 v[246:247], v[104:105], s[12:13], v[246:247] op_sel_hi:[1,0,1]
	v_pk_fma_f32 v[104:105], v[104:105], s[76:77], v[246:247] op_sel_hi:[1,0,1]
	s_mov_b64 s[4:5], 0
	global_store_dwordx4 v[152:153], v[98:101], off nt
	global_store_dwordx4 v[152:153], v[102:105], off offset:16 nt

.LBB0_844:
	s_nop 1
	v_mad_i64_i32 v[98:99], s[0:1], v114, s33, 0
	v_lshl_add_u64 v[114:115], v[98:99], 0, v[124:125]
	s_cmp_gt_i32 s71, 8
	s_mov_b64 s[0:1], -1
	s_cbranch_scc1 .LBB0_850
	s_cmp_lt_u32 s73, 5
	s_cselect_b64 s[0:1], -1, 0
	s_cmp_gt_u32 s73, 4
	s_cbranch_scc0 .LBB0_850
	s_andn2_b64 vcc, exec, s[28:29]
	s_mov_b64 s[4:5], -1
	s_cbranch_vccnz .LBB0_848
	s_mov_b32 s4, 0x3fb8aa3b
	s_mov_b32 s76, 0x3f317217
	s_mov_b32 s12, 0x3377d1cf
	v_lshl_add_u64 v[116:117], v[114:115], 2, s[86:87]
	v_pk_mul_f32 v[98:99], v[112:113], s[4:5] op_sel_hi:[1,0]
	v_pk_mul_f32 v[100:101], v[110:111], s[4:5] op_sel_hi:[1,0]
	v_pk_mul_f32 v[102:103], v[108:109], s[4:5] op_sel_hi:[1,0]
	v_pk_mul_f32 v[104:105], v[106:107], s[4:5] op_sel_hi:[1,0]
	v_exp_f32_e32 v98, v98
	v_exp_f32_e32 v99, v99
	v_exp_f32_e32 v100, v100
	v_exp_f32_e32 v101, v101
	v_exp_f32_e32 v102, v102
	v_exp_f32_e32 v103, v103
	v_exp_f32_e32 v104, v104
	v_exp_f32_e32 v105, v105
	v_pk_add_f32 v[98:99], v[98:99], 1.0 op_sel_hi:[1,0]
	v_pk_add_f32 v[100:101], v[100:101], 1.0 op_sel_hi:[1,0]
	v_pk_add_f32 v[102:103], v[102:103], 1.0 op_sel_hi:[1,0]
	v_pk_add_f32 v[104:105], v[104:105], 1.0 op_sel_hi:[1,0]
	v_rcp_f32_e32 v98, v98
	v_rcp_f32_e32 v99, v99
	v_rcp_f32_e32 v100, v100
	v_rcp_f32_e32 v101, v101
	v_rcp_f32_e32 v102, v102
	v_rcp_f32_e32 v103, v103
	v_rcp_f32_e32 v104, v104
	v_rcp_f32_e32 v105, v105
	v_pk_mul_f32 v[98:99], v[98:99], v[228:229]
	v_pk_mul_f32 v[100:101], v[100:101], v[230:231]
	v_pk_mul_f32 v[102:103], v[102:103], v[232:233]
	v_pk_mul_f32 v[104:105], v[104:105], v[234:235]
	v_min_f32_e32 v98, 0x3f7fffef, v98
	v_min_f32_e32 v99, 0x3f7fffef, v99
	v_min_f32_e32 v100, 0x3f7fffef, v100
	v_min_f32_e32 v101, 0x3f7fffef, v101
	v_min_f32_e32 v102, 0x3f7fffef, v102
	v_min_f32_e32 v103, 0x3f7fffef, v103
	v_min_f32_e32 v104, 0x3f7fffef, v104
	v_min_f32_e32 v105, 0x3f7fffef, v105
	v_pk_add_f32 v[98:99], v[98:99], 1.0 op_sel_hi:[1,0] neg_lo:[1,0] neg_hi:[1,0]
	v_pk_add_f32 v[100:101], v[100:101], 1.0 op_sel_hi:[1,0] neg_lo:[1,0] neg_hi:[1,0]
	v_pk_add_f32 v[102:103], v[102:103], 1.0 op_sel_hi:[1,0] neg_lo:[1,0] neg_hi:[1,0]
	v_pk_add_f32 v[104:105], v[104:105], 1.0 op_sel_hi:[1,0] neg_lo:[1,0] neg_hi:[1,0]
	v_log_f32_e32 v98, v98
	v_log_f32_e32 v99, v99
	v_log_f32_e32 v100, v100
	v_log_f32_e32 v101, v101
	v_log_f32_e32 v102, v102
	v_log_f32_e32 v103, v103
	v_log_f32_e32 v104, v104
	v_log_f32_e32 v105, v105
	v_pk_mul_f32 v[244:245], v[98:99], s[76:77] op_sel_hi:[1,0]
	v_pk_fma_f32 v[244:245], v[98:99], s[76:77], v[244:245] op_sel_hi:[1,0,1] neg_lo:[0,0,1] neg_hi:[0,0,1]
	v_pk_fma_f32 v[244:245], v[98:99], s[12:13], v[244:245] op_sel_hi:[1,0,1]
	v_pk_fma_f32 v[98:99], v[98:99], s[76:77], v[244:245] op_sel_hi:[1,0,1]
	v_pk_mul_f32 v[246:247], v[100:101], s[76:77] op_sel_hi:[1,0]
	v_pk_fma_f32 v[246:247], v[100:101], s[76:77], v[246:247] op_sel_hi:[1,0,1] neg_lo:[0,0,1] neg_hi:[0,0,1]
	v_pk_fma_f32 v[246:247], v[100:101], s[12:13], v[246:247] op_sel_hi:[1,0,1]
	v_pk_fma_f32 v[100:101], v[100:101], s[76:77], v[246:247] op_sel_hi:[1,0,1]
	v_pk_mul_f32 v[244:245], v[102:103], s[76:77] op_sel_hi:[1,0]
	v_pk_fma_f32 v[244:245], v[102:103], s[76:77], v[244:245] op_sel_hi:[1,0,1] neg_lo:[0,0,1] neg_hi:[0,0,1]
	v_pk_fma_f32 v[244:245], v[102:103], s[12:13], v[244:245] op_sel_hi:[1,0,1]
	v_pk_fma_f32 v[102:103], v[102:103], s[76:77], v[244:245] op_sel_hi:[1,0,1]
	v_pk_mul_f32 v[246:247], v[104:105], s[76:77] op_sel_hi:[1,0]
	v_pk_fma_f32 v[246:247], v[104:105], s[76:77], v[246:247] op_sel_hi:[1,0,1] neg_lo:[0,0,1] neg_hi:[0,0,1]
	v_pk_fma_f32 v[246:247], v[104:105], s[12:13], v[246:247] op_sel_hi:[1,0,1]
	v_pk_fma_f32 v[104:105], v[104:105], s[76:77], v[246:247] op_sel_hi:[1,0,1]
	s_mov_b64 s[4:5], 0
	global_store_dwordx4 v[116:117], v[98:101], off nt
	global_store_dwordx4 v[116:117], v[102:105], off offset:16 nt

.LBB0_854:
	s_andn2_b64 vcc, exec, s[0:1]
	s_cbranch_vccnz .LBB0_871
	v_mad_i64_i32 v[108:109], s[0:1], v98, s33, v[122:123]
	s_cmp_gt_i32 s71, 8
	s_mov_b64 s[0:1], -1
	s_cbranch_scc1 .LBB0_861
	s_cmp_lt_u32 s73, 5
	s_cselect_b64 s[0:1], -1, 0
	s_cmp_gt_u32 s73, 4
	s_cbranch_scc0 .LBB0_861
	s_andn2_b64 vcc, exec, s[28:29]
	s_mov_b64 s[4:5], -1
	s_cbranch_vccnz .LBB0_859
	s_mov_b32 s4, 0x3fb8aa3b
	s_mov_b32 s76, 0x3f317217
	s_mov_b32 s12, 0x3377d1cf
	v_lshl_add_u64 v[110:111], v[108:109], 2, s[86:87]
	v_pk_mul_f32 v[82:83], v[106:107], s[4:5] op_sel_hi:[1,0]
	v_pk_mul_f32 v[84:85], v[104:105], s[4:5] op_sel_hi:[1,0]
	v_pk_mul_f32 v[86:87], v[102:103], s[4:5] op_sel_hi:[1,0]
	v_pk_mul_f32 v[88:89], v[100:101], s[4:5] op_sel_hi:[1,0]
	v_exp_f32_e32 v82, v82
	v_exp_f32_e32 v83, v83
	v_exp_f32_e32 v84, v84
	v_exp_f32_e32 v85, v85
	v_exp_f32_e32 v86, v86
	v_exp_f32_e32 v87, v87
	v_exp_f32_e32 v88, v88
	v_exp_f32_e32 v89, v89
	v_pk_add_f32 v[82:83], v[82:83], 1.0 op_sel_hi:[1,0]
	v_pk_add_f32 v[84:85], v[84:85], 1.0 op_sel_hi:[1,0]
	v_pk_add_f32 v[86:87], v[86:87], 1.0 op_sel_hi:[1,0]
	v_pk_add_f32 v[88:89], v[88:89], 1.0 op_sel_hi:[1,0]
	v_rcp_f32_e32 v82, v82
	v_rcp_f32_e32 v83, v83
	v_rcp_f32_e32 v84, v84
	v_rcp_f32_e32 v85, v85
	v_rcp_f32_e32 v86, v86
	v_rcp_f32_e32 v87, v87
	v_rcp_f32_e32 v88, v88
	v_rcp_f32_e32 v89, v89
	v_pk_mul_f32 v[82:83], v[82:83], v[220:221]
	v_pk_mul_f32 v[84:85], v[84:85], v[222:223]
	v_pk_mul_f32 v[86:87], v[86:87], v[224:225]
	v_pk_mul_f32 v[88:89], v[88:89], v[226:227]
	v_min_f32_e32 v82, 0x3f7fffef, v82
	v_min_f32_e32 v83, 0x3f7fffef, v83
	v_min_f32_e32 v84, 0x3f7fffef, v84
	v_min_f32_e32 v85, 0x3f7fffef, v85
	v_min_f32_e32 v86, 0x3f7fffef, v86
	v_min_f32_e32 v87, 0x3f7fffef, v87
	v_min_f32_e32 v88, 0x3f7fffef, v88
	v_min_f32_e32 v89, 0x3f7fffef, v89
	v_pk_add_f32 v[82:83], v[82:83], 1.0 op_sel_hi:[1,0] neg_lo:[1,0] neg_hi:[1,0]
	v_pk_add_f32 v[84:85], v[84:85], 1.0 op_sel_hi:[1,0] neg_lo:[1,0] neg_hi:[1,0]
	v_pk_add_f32 v[86:87], v[86:87], 1.0 op_sel_hi:[1,0] neg_lo:[1,0] neg_hi:[1,0]
	v_pk_add_f32 v[88:89], v[88:89], 1.0 op_sel_hi:[1,0] neg_lo:[1,0] neg_hi:[1,0]
	v_log_f32_e32 v82, v82
	v_log_f32_e32 v83, v83
	v_log_f32_e32 v84, v84
	v_log_f32_e32 v85, v85
	v_log_f32_e32 v86, v86
	v_log_f32_e32 v87, v87
	v_log_f32_e32 v88, v88
	v_log_f32_e32 v89, v89
	v_pk_mul_f32 v[244:245], v[82:83], s[76:77] op_sel_hi:[1,0]
	v_pk_fma_f32 v[244:245], v[82:83], s[76:77], v[244:245] op_sel_hi:[1,0,1] neg_lo:[0,0,1] neg_hi:[0,0,1]
	v_pk_fma_f32 v[244:245], v[82:83], s[12:13], v[244:245] op_sel_hi:[1,0,1]
	v_pk_fma_f32 v[82:83], v[82:83], s[76:77], v[244:245] op_sel_hi:[1,0,1]
	v_pk_mul_f32 v[246:247], v[84:85], s[76:77] op_sel_hi:[1,0]
	v_pk_fma_f32 v[246:247], v[84:85], s[76:77], v[246:247] op_sel_hi:[1,0,1] neg_lo:[0,0,1] neg_hi:[0,0,1]
	v_pk_fma_f32 v[246:247], v[84:85], s[12:13], v[246:247] op_sel_hi:[1,0,1]
	v_pk_fma_f32 v[84:85], v[84:85], s[76:77], v[246:247] op_sel_hi:[1,0,1]
	v_pk_mul_f32 v[244:245], v[86:87], s[76:77] op_sel_hi:[1,0]
	v_pk_fma_f32 v[244:245], v[86:87], s[76:77], v[244:245] op_sel_hi:[1,0,1] neg_lo:[0,0,1] neg_hi:[0,0,1]
	v_pk_fma_f32 v[244:245], v[86:87], s[12:13], v[244:245] op_sel_hi:[1,0,1]
	v_pk_fma_f32 v[86:87], v[86:87], s[76:77], v[244:245] op_sel_hi:[1,0,1]
	v_pk_mul_f32 v[246:247], v[88:89], s[76:77] op_sel_hi:[1,0]
	v_pk_fma_f32 v[246:247], v[88:89], s[76:77], v[246:247] op_sel_hi:[1,0,1] neg_lo:[0,0,1] neg_hi:[0,0,1]
	v_pk_fma_f32 v[246:247], v[88:89], s[12:13], v[246:247] op_sel_hi:[1,0,1]
	v_pk_fma_f32 v[88:89], v[88:89], s[76:77], v[246:247] op_sel_hi:[1,0,1]
	s_mov_b64 s[4:5], 0
	global_store_dwordx4 v[110:111], v[82:85], off nt
	global_store_dwordx4 v[110:111], v[86:89], off offset:16 nt

.LBB0_863:
	s_nop 1
	v_mad_i64_i32 v[82:83], s[0:1], v98, s33, 0
	v_lshl_add_u64 v[98:99], v[82:83], 0, v[124:125]
	s_cmp_gt_i32 s71, 8
	s_mov_b64 s[0:1], -1
	s_cbranch_scc1 .LBB0_869
	s_cmp_lt_u32 s73, 5
	s_cselect_b64 s[0:1], -1, 0
	s_cmp_gt_u32 s73, 4
	s_cbranch_scc0 .LBB0_869
	s_andn2_b64 vcc, exec, s[28:29]
	s_mov_b64 s[4:5], -1
	s_cbranch_vccnz .LBB0_867
	s_mov_b32 s4, 0x3fb8aa3b
	s_mov_b32 s76, 0x3f317217
	s_mov_b32 s12, 0x3377d1cf
	v_lshl_add_u64 v[100:101], v[98:99], 2, s[86:87]
	v_pk_mul_f32 v[82:83], v[96:97], s[4:5] op_sel_hi:[1,0]
	v_pk_mul_f32 v[84:85], v[94:95], s[4:5] op_sel_hi:[1,0]
	v_pk_mul_f32 v[86:87], v[92:93], s[4:5] op_sel_hi:[1,0]
	v_pk_mul_f32 v[88:89], v[90:91], s[4:5] op_sel_hi:[1,0]
	v_exp_f32_e32 v82, v82
	v_exp_f32_e32 v83, v83
	v_exp_f32_e32 v84, v84
	v_exp_f32_e32 v85, v85
	v_exp_f32_e32 v86, v86
	v_exp_f32_e32 v87, v87
	v_exp_f32_e32 v88, v88
	v_exp_f32_e32 v89, v89
	v_pk_add_f32 v[82:83], v[82:83], 1.0 op_sel_hi:[1,0]
	v_pk_add_f32 v[84:85], v[84:85], 1.0 op_sel_hi:[1,0]
	v_pk_add_f32 v[86:87], v[86:87], 1.0 op_sel_hi:[1,0]
	v_pk_add_f32 v[88:89], v[88:89], 1.0 op_sel_hi:[1,0]
	v_rcp_f32_e32 v82, v82
	v_rcp_f32_e32 v83, v83
	v_rcp_f32_e32 v84, v84
	v_rcp_f32_e32 v85, v85
	v_rcp_f32_e32 v86, v86
	v_rcp_f32_e32 v87, v87
	v_rcp_f32_e32 v88, v88
	v_rcp_f32_e32 v89, v89
	v_pk_mul_f32 v[82:83], v[82:83], v[228:229]
	v_pk_mul_f32 v[84:85], v[84:85], v[230:231]
	v_pk_mul_f32 v[86:87], v[86:87], v[232:233]
	v_pk_mul_f32 v[88:89], v[88:89], v[234:235]
	v_min_f32_e32 v82, 0x3f7fffef, v82
	v_min_f32_e32 v83, 0x3f7fffef, v83
	v_min_f32_e32 v84, 0x3f7fffef, v84
	v_min_f32_e32 v85, 0x3f7fffef, v85
	v_min_f32_e32 v86, 0x3f7fffef, v86
	v_min_f32_e32 v87, 0x3f7fffef, v87
	v_min_f32_e32 v88, 0x3f7fffef, v88
	v_min_f32_e32 v89, 0x3f7fffef, v89
	v_pk_add_f32 v[82:83], v[82:83], 1.0 op_sel_hi:[1,0] neg_lo:[1,0] neg_hi:[1,0]
	v_pk_add_f32 v[84:85], v[84:85], 1.0 op_sel_hi:[1,0] neg_lo:[1,0] neg_hi:[1,0]
	v_pk_add_f32 v[86:87], v[86:87], 1.0 op_sel_hi:[1,0] neg_lo:[1,0] neg_hi:[1,0]
	v_pk_add_f32 v[88:89], v[88:89], 1.0 op_sel_hi:[1,0] neg_lo:[1,0] neg_hi:[1,0]
	v_log_f32_e32 v82, v82
	v_log_f32_e32 v83, v83
	v_log_f32_e32 v84, v84
	v_log_f32_e32 v85, v85
	v_log_f32_e32 v86, v86
	v_log_f32_e32 v87, v87
	v_log_f32_e32 v88, v88
	v_log_f32_e32 v89, v89
	v_pk_mul_f32 v[244:245], v[82:83], s[76:77] op_sel_hi:[1,0]
	v_pk_fma_f32 v[244:245], v[82:83], s[76:77], v[244:245] op_sel_hi:[1,0,1] neg_lo:[0,0,1] neg_hi:[0,0,1]
	v_pk_fma_f32 v[244:245], v[82:83], s[12:13], v[244:245] op_sel_hi:[1,0,1]
	v_pk_fma_f32 v[82:83], v[82:83], s[76:77], v[244:245] op_sel_hi:[1,0,1]
	v_pk_mul_f32 v[246:247], v[84:85], s[76:77] op_sel_hi:[1,0]
	v_pk_fma_f32 v[246:247], v[84:85], s[76:77], v[246:247] op_sel_hi:[1,0,1] neg_lo:[0,0,1] neg_hi:[0,0,1]
	v_pk_fma_f32 v[246:247], v[84:85], s[12:13], v[246:247] op_sel_hi:[1,0,1]
	v_pk_fma_f32 v[84:85], v[84:85], s[76:77], v[246:247] op_sel_hi:[1,0,1]
	v_pk_mul_f32 v[244:245], v[86:87], s[76:77] op_sel_hi:[1,0]
	v_pk_fma_f32 v[244:245], v[86:87], s[76:77], v[244:245] op_sel_hi:[1,0,1] neg_lo:[0,0,1] neg_hi:[0,0,1]
	v_pk_fma_f32 v[244:245], v[86:87], s[12:13], v[244:245] op_sel_hi:[1,0,1]
	v_pk_fma_f32 v[86:87], v[86:87], s[76:77], v[244:245] op_sel_hi:[1,0,1]
	v_pk_mul_f32 v[246:247], v[88:89], s[76:77] op_sel_hi:[1,0]
	v_pk_fma_f32 v[246:247], v[88:89], s[76:77], v[246:247] op_sel_hi:[1,0,1] neg_lo:[0,0,1] neg_hi:[0,0,1]
	v_pk_fma_f32 v[246:247], v[88:89], s[12:13], v[246:247] op_sel_hi:[1,0,1]
	v_pk_fma_f32 v[88:89], v[88:89], s[76:77], v[246:247] op_sel_hi:[1,0,1]
	s_mov_b64 s[4:5], 0
	global_store_dwordx4 v[100:101], v[82:85], off nt
	global_store_dwordx4 v[100:101], v[86:89], off offset:16 nt

.LBB0_873:
	s_andn2_b64 vcc, exec, s[0:1]
	s_cbranch_vccnz .LBB0_890
	v_mad_i64_i32 v[92:93], s[0:1], v82, s33, v[122:123]
	s_cmp_gt_i32 s71, 8
	s_mov_b64 s[0:1], -1
	s_cbranch_scc1 .LBB0_880
	s_cmp_lt_u32 s73, 5
	s_cselect_b64 s[0:1], -1, 0
	s_cmp_gt_u32 s73, 4
	s_cbranch_scc0 .LBB0_880
	s_andn2_b64 vcc, exec, s[28:29]
	s_mov_b64 s[4:5], -1
	s_cbranch_vccnz .LBB0_878
	s_mov_b32 s4, 0x3fb8aa3b
	s_mov_b32 s76, 0x3f317217
	s_mov_b32 s12, 0x3377d1cf
	v_lshl_add_u64 v[94:95], v[92:93], 2, s[86:87]
	v_pk_mul_f32 v[66:67], v[90:91], s[4:5] op_sel_hi:[1,0]
	v_pk_mul_f32 v[68:69], v[88:89], s[4:5] op_sel_hi:[1,0]
	v_pk_mul_f32 v[70:71], v[86:87], s[4:5] op_sel_hi:[1,0]
	v_pk_mul_f32 v[72:73], v[84:85], s[4:5] op_sel_hi:[1,0]
	v_exp_f32_e32 v66, v66
	v_exp_f32_e32 v67, v67
	v_exp_f32_e32 v68, v68
	v_exp_f32_e32 v69, v69
	v_exp_f32_e32 v70, v70
	v_exp_f32_e32 v71, v71
	v_exp_f32_e32 v72, v72
	v_exp_f32_e32 v73, v73
	v_pk_add_f32 v[66:67], v[66:67], 1.0 op_sel_hi:[1,0]
	v_pk_add_f32 v[68:69], v[68:69], 1.0 op_sel_hi:[1,0]
	v_pk_add_f32 v[70:71], v[70:71], 1.0 op_sel_hi:[1,0]
	v_pk_add_f32 v[72:73], v[72:73], 1.0 op_sel_hi:[1,0]
	v_rcp_f32_e32 v66, v66
	v_rcp_f32_e32 v67, v67
	v_rcp_f32_e32 v68, v68
	v_rcp_f32_e32 v69, v69
	v_rcp_f32_e32 v70, v70
	v_rcp_f32_e32 v71, v71
	v_rcp_f32_e32 v72, v72
	v_rcp_f32_e32 v73, v73
	v_pk_mul_f32 v[66:67], v[66:67], v[220:221]
	v_pk_mul_f32 v[68:69], v[68:69], v[222:223]
	v_pk_mul_f32 v[70:71], v[70:71], v[224:225]
	v_pk_mul_f32 v[72:73], v[72:73], v[226:227]
	v_min_f32_e32 v66, 0x3f7fffef, v66
	v_min_f32_e32 v67, 0x3f7fffef, v67
	v_min_f32_e32 v68, 0x3f7fffef, v68
	v_min_f32_e32 v69, 0x3f7fffef, v69
	v_min_f32_e32 v70, 0x3f7fffef, v70
	v_min_f32_e32 v71, 0x3f7fffef, v71
	v_min_f32_e32 v72, 0x3f7fffef, v72
	v_min_f32_e32 v73, 0x3f7fffef, v73
	v_pk_add_f32 v[66:67], v[66:67], 1.0 op_sel_hi:[1,0] neg_lo:[1,0] neg_hi:[1,0]
	v_pk_add_f32 v[68:69], v[68:69], 1.0 op_sel_hi:[1,0] neg_lo:[1,0] neg_hi:[1,0]
	v_pk_add_f32 v[70:71], v[70:71], 1.0 op_sel_hi:[1,0] neg_lo:[1,0] neg_hi:[1,0]
	v_pk_add_f32 v[72:73], v[72:73], 1.0 op_sel_hi:[1,0] neg_lo:[1,0] neg_hi:[1,0]
	v_log_f32_e32 v66, v66
	v_log_f32_e32 v67, v67
	v_log_f32_e32 v68, v68
	v_log_f32_e32 v69, v69
	v_log_f32_e32 v70, v70
	v_log_f32_e32 v71, v71
	v_log_f32_e32 v72, v72
	v_log_f32_e32 v73, v73
	v_pk_mul_f32 v[244:245], v[66:67], s[76:77] op_sel_hi:[1,0]
	v_pk_fma_f32 v[244:245], v[66:67], s[76:77], v[244:245] op_sel_hi:[1,0,1] neg_lo:[0,0,1] neg_hi:[0,0,1]
	v_pk_fma_f32 v[244:245], v[66:67], s[12:13], v[244:245] op_sel_hi:[1,0,1]
	v_pk_fma_f32 v[66:67], v[66:67], s[76:77], v[244:245] op_sel_hi:[1,0,1]
	v_pk_mul_f32 v[246:247], v[68:69], s[76:77] op_sel_hi:[1,0]
	v_pk_fma_f32 v[246:247], v[68:69], s[76:77], v[246:247] op_sel_hi:[1,0,1] neg_lo:[0,0,1] neg_hi:[0,0,1]
	v_pk_fma_f32 v[246:247], v[68:69], s[12:13], v[246:247] op_sel_hi:[1,0,1]
	v_pk_fma_f32 v[68:69], v[68:69], s[76:77], v[246:247] op_sel_hi:[1,0,1]
	v_pk_mul_f32 v[244:245], v[70:71], s[76:77] op_sel_hi:[1,0]
	v_pk_fma_f32 v[244:245], v[70:71], s[76:77], v[244:245] op_sel_hi:[1,0,1] neg_lo:[0,0,1] neg_hi:[0,0,1]
	v_pk_fma_f32 v[244:245], v[70:71], s[12:13], v[244:245] op_sel_hi:[1,0,1]
	v_pk_fma_f32 v[70:71], v[70:71], s[76:77], v[244:245] op_sel_hi:[1,0,1]
	v_pk_mul_f32 v[246:247], v[72:73], s[76:77] op_sel_hi:[1,0]
	v_pk_fma_f32 v[246:247], v[72:73], s[76:77], v[246:247] op_sel_hi:[1,0,1] neg_lo:[0,0,1] neg_hi:[0,0,1]
	v_pk_fma_f32 v[246:247], v[72:73], s[12:13], v[246:247] op_sel_hi:[1,0,1]
	v_pk_fma_f32 v[72:73], v[72:73], s[76:77], v[246:247] op_sel_hi:[1,0,1]
	s_mov_b64 s[4:5], 0
	global_store_dwordx4 v[94:95], v[66:69], off nt
	global_store_dwordx4 v[94:95], v[70:73], off offset:16 nt

.LBB0_882:
	s_nop 1
	v_mad_i64_i32 v[66:67], s[0:1], v82, s33, 0
	v_lshl_add_u64 v[82:83], v[66:67], 0, v[124:125]
	s_cmp_gt_i32 s71, 8
	s_mov_b64 s[0:1], -1
	s_cbranch_scc1 .LBB0_888
	s_cmp_lt_u32 s73, 5
	s_cselect_b64 s[0:1], -1, 0
	s_cmp_gt_u32 s73, 4
	s_cbranch_scc0 .LBB0_888
	s_andn2_b64 vcc, exec, s[28:29]
	s_mov_b64 s[4:5], -1
	s_cbranch_vccnz .LBB0_886
	s_mov_b32 s4, 0x3fb8aa3b
	s_mov_b32 s76, 0x3f317217
	s_mov_b32 s12, 0x3377d1cf
	v_lshl_add_u64 v[84:85], v[82:83], 2, s[86:87]
	v_pk_mul_f32 v[66:67], v[80:81], s[4:5] op_sel_hi:[1,0]
	v_pk_mul_f32 v[68:69], v[78:79], s[4:5] op_sel_hi:[1,0]
	v_pk_mul_f32 v[70:71], v[76:77], s[4:5] op_sel_hi:[1,0]
	v_pk_mul_f32 v[72:73], v[74:75], s[4:5] op_sel_hi:[1,0]
	v_exp_f32_e32 v66, v66
	v_exp_f32_e32 v67, v67
	v_exp_f32_e32 v68, v68
	v_exp_f32_e32 v69, v69
	v_exp_f32_e32 v70, v70
	v_exp_f32_e32 v71, v71
	v_exp_f32_e32 v72, v72
	v_exp_f32_e32 v73, v73
	v_pk_add_f32 v[66:67], v[66:67], 1.0 op_sel_hi:[1,0]
	v_pk_add_f32 v[68:69], v[68:69], 1.0 op_sel_hi:[1,0]
	v_pk_add_f32 v[70:71], v[70:71], 1.0 op_sel_hi:[1,0]
	v_pk_add_f32 v[72:73], v[72:73], 1.0 op_sel_hi:[1,0]
	v_rcp_f32_e32 v66, v66
	v_rcp_f32_e32 v67, v67
	v_rcp_f32_e32 v68, v68
	v_rcp_f32_e32 v69, v69
	v_rcp_f32_e32 v70, v70
	v_rcp_f32_e32 v71, v71
	v_rcp_f32_e32 v72, v72
	v_rcp_f32_e32 v73, v73
	v_pk_mul_f32 v[66:67], v[66:67], v[228:229]
	v_pk_mul_f32 v[68:69], v[68:69], v[230:231]
	v_pk_mul_f32 v[70:71], v[70:71], v[232:233]
	v_pk_mul_f32 v[72:73], v[72:73], v[234:235]
	v_min_f32_e32 v66, 0x3f7fffef, v66
	v_min_f32_e32 v67, 0x3f7fffef, v67
	v_min_f32_e32 v68, 0x3f7fffef, v68
	v_min_f32_e32 v69, 0x3f7fffef, v69
	v_min_f32_e32 v70, 0x3f7fffef, v70
	v_min_f32_e32 v71, 0x3f7fffef, v71
	v_min_f32_e32 v72, 0x3f7fffef, v72
	v_min_f32_e32 v73, 0x3f7fffef, v73
	v_pk_add_f32 v[66:67], v[66:67], 1.0 op_sel_hi:[1,0] neg_lo:[1,0] neg_hi:[1,0]
	v_pk_add_f32 v[68:69], v[68:69], 1.0 op_sel_hi:[1,0] neg_lo:[1,0] neg_hi:[1,0]
	v_pk_add_f32 v[70:71], v[70:71], 1.0 op_sel_hi:[1,0] neg_lo:[1,0] neg_hi:[1,0]
	v_pk_add_f32 v[72:73], v[72:73], 1.0 op_sel_hi:[1,0] neg_lo:[1,0] neg_hi:[1,0]
	v_log_f32_e32 v66, v66
	v_log_f32_e32 v67, v67
	v_log_f32_e32 v68, v68
	v_log_f32_e32 v69, v69
	v_log_f32_e32 v70, v70
	v_log_f32_e32 v71, v71
	v_log_f32_e32 v72, v72
	v_log_f32_e32 v73, v73
	v_pk_mul_f32 v[244:245], v[66:67], s[76:77] op_sel_hi:[1,0]
	v_pk_fma_f32 v[244:245], v[66:67], s[76:77], v[244:245] op_sel_hi:[1,0,1] neg_lo:[0,0,1] neg_hi:[0,0,1]
	v_pk_fma_f32 v[244:245], v[66:67], s[12:13], v[244:245] op_sel_hi:[1,0,1]
	v_pk_fma_f32 v[66:67], v[66:67], s[76:77], v[244:245] op_sel_hi:[1,0,1]
	v_pk_mul_f32 v[246:247], v[68:69], s[76:77] op_sel_hi:[1,0]
	v_pk_fma_f32 v[246:247], v[68:69], s[76:77], v[246:247] op_sel_hi:[1,0,1] neg_lo:[0,0,1] neg_hi:[0,0,1]
	v_pk_fma_f32 v[246:247], v[68:69], s[12:13], v[246:247] op_sel_hi:[1,0,1]
	v_pk_fma_f32 v[68:69], v[68:69], s[76:77], v[246:247] op_sel_hi:[1,0,1]
	v_pk_mul_f32 v[244:245], v[70:71], s[76:77] op_sel_hi:[1,0]
	v_pk_fma_f32 v[244:245], v[70:71], s[76:77], v[244:245] op_sel_hi:[1,0,1] neg_lo:[0,0,1] neg_hi:[0,0,1]
	v_pk_fma_f32 v[244:245], v[70:71], s[12:13], v[244:245] op_sel_hi:[1,0,1]
	v_pk_fma_f32 v[70:71], v[70:71], s[76:77], v[244:245] op_sel_hi:[1,0,1]
	v_pk_mul_f32 v[246:247], v[72:73], s[76:77] op_sel_hi:[1,0]
	v_pk_fma_f32 v[246:247], v[72:73], s[76:77], v[246:247] op_sel_hi:[1,0,1] neg_lo:[0,0,1] neg_hi:[0,0,1]
	v_pk_fma_f32 v[246:247], v[72:73], s[12:13], v[246:247] op_sel_hi:[1,0,1]
	v_pk_fma_f32 v[72:73], v[72:73], s[76:77], v[246:247] op_sel_hi:[1,0,1]
	s_mov_b64 s[4:5], 0
	global_store_dwordx4 v[84:85], v[66:69], off nt
	global_store_dwordx4 v[84:85], v[70:73], off offset:16 nt

.LBB0_892:
	s_andn2_b64 vcc, exec, s[0:1]
	s_cbranch_vccnz .LBB0_909
	v_mad_i64_i32 v[76:77], s[0:1], v66, s33, v[122:123]
	s_cmp_gt_i32 s71, 8
	s_mov_b64 s[0:1], -1
	s_cbranch_scc1 .LBB0_899
	s_cmp_lt_u32 s73, 5
	s_cselect_b64 s[0:1], -1, 0
	s_cmp_gt_u32 s73, 4
	s_cbranch_scc0 .LBB0_899
	s_andn2_b64 vcc, exec, s[28:29]
	s_mov_b64 s[4:5], -1
	s_cbranch_vccnz .LBB0_897
	s_mov_b32 s4, 0x3fb8aa3b
	s_mov_b32 s76, 0x3f317217
	s_mov_b32 s12, 0x3377d1cf
	v_lshl_add_u64 v[78:79], v[76:77], 2, s[86:87]
	v_pk_mul_f32 v[50:51], v[74:75], s[4:5] op_sel_hi:[1,0]
	v_pk_mul_f32 v[52:53], v[72:73], s[4:5] op_sel_hi:[1,0]
	v_pk_mul_f32 v[54:55], v[70:71], s[4:5] op_sel_hi:[1,0]
	v_pk_mul_f32 v[56:57], v[68:69], s[4:5] op_sel_hi:[1,0]
	v_exp_f32_e32 v50, v50
	v_exp_f32_e32 v51, v51
	v_exp_f32_e32 v52, v52
	v_exp_f32_e32 v53, v53
	v_exp_f32_e32 v54, v54
	v_exp_f32_e32 v55, v55
	v_exp_f32_e32 v56, v56
	v_exp_f32_e32 v57, v57
	v_pk_add_f32 v[50:51], v[50:51], 1.0 op_sel_hi:[1,0]
	v_pk_add_f32 v[52:53], v[52:53], 1.0 op_sel_hi:[1,0]
	v_pk_add_f32 v[54:55], v[54:55], 1.0 op_sel_hi:[1,0]
	v_pk_add_f32 v[56:57], v[56:57], 1.0 op_sel_hi:[1,0]
	v_rcp_f32_e32 v50, v50
	v_rcp_f32_e32 v51, v51
	v_rcp_f32_e32 v52, v52
	v_rcp_f32_e32 v53, v53
	v_rcp_f32_e32 v54, v54
	v_rcp_f32_e32 v55, v55
	v_rcp_f32_e32 v56, v56
	v_rcp_f32_e32 v57, v57
	v_pk_mul_f32 v[50:51], v[50:51], v[220:221]
	v_pk_mul_f32 v[52:53], v[52:53], v[222:223]
	v_pk_mul_f32 v[54:55], v[54:55], v[224:225]
	v_pk_mul_f32 v[56:57], v[56:57], v[226:227]
	v_min_f32_e32 v50, 0x3f7fffef, v50
	v_min_f32_e32 v51, 0x3f7fffef, v51
	v_min_f32_e32 v52, 0x3f7fffef, v52
	v_min_f32_e32 v53, 0x3f7fffef, v53
	v_min_f32_e32 v54, 0x3f7fffef, v54
	v_min_f32_e32 v55, 0x3f7fffef, v55
	v_min_f32_e32 v56, 0x3f7fffef, v56
	v_min_f32_e32 v57, 0x3f7fffef, v57
	v_pk_add_f32 v[50:51], v[50:51], 1.0 op_sel_hi:[1,0] neg_lo:[1,0] neg_hi:[1,0]
	v_pk_add_f32 v[52:53], v[52:53], 1.0 op_sel_hi:[1,0] neg_lo:[1,0] neg_hi:[1,0]
	v_pk_add_f32 v[54:55], v[54:55], 1.0 op_sel_hi:[1,0] neg_lo:[1,0] neg_hi:[1,0]
	v_pk_add_f32 v[56:57], v[56:57], 1.0 op_sel_hi:[1,0] neg_lo:[1,0] neg_hi:[1,0]
	v_log_f32_e32 v50, v50
	v_log_f32_e32 v51, v51
	v_log_f32_e32 v52, v52
	v_log_f32_e32 v53, v53
	v_log_f32_e32 v54, v54
	v_log_f32_e32 v55, v55
	v_log_f32_e32 v56, v56
	v_log_f32_e32 v57, v57
	v_pk_mul_f32 v[244:245], v[50:51], s[76:77] op_sel_hi:[1,0]
	v_pk_fma_f32 v[244:245], v[50:51], s[76:77], v[244:245] op_sel_hi:[1,0,1] neg_lo:[0,0,1] neg_hi:[0,0,1]
	v_pk_fma_f32 v[244:245], v[50:51], s[12:13], v[244:245] op_sel_hi:[1,0,1]
	v_pk_fma_f32 v[50:51], v[50:51], s[76:77], v[244:245] op_sel_hi:[1,0,1]
	v_pk_mul_f32 v[246:247], v[52:53], s[76:77] op_sel_hi:[1,0]
	v_pk_fma_f32 v[246:247], v[52:53], s[76:77], v[246:247] op_sel_hi:[1,0,1] neg_lo:[0,0,1] neg_hi:[0,0,1]
	v_pk_fma_f32 v[246:247], v[52:53], s[12:13], v[246:247] op_sel_hi:[1,0,1]
	v_pk_fma_f32 v[52:53], v[52:53], s[76:77], v[246:247] op_sel_hi:[1,0,1]
	v_pk_mul_f32 v[244:245], v[54:55], s[76:77] op_sel_hi:[1,0]
	v_pk_fma_f32 v[244:245], v[54:55], s[76:77], v[244:245] op_sel_hi:[1,0,1] neg_lo:[0,0,1] neg_hi:[0,0,1]
	v_pk_fma_f32 v[244:245], v[54:55], s[12:13], v[244:245] op_sel_hi:[1,0,1]
	v_pk_fma_f32 v[54:55], v[54:55], s[76:77], v[244:245] op_sel_hi:[1,0,1]
	v_pk_mul_f32 v[246:247], v[56:57], s[76:77] op_sel_hi:[1,0]
	v_pk_fma_f32 v[246:247], v[56:57], s[76:77], v[246:247] op_sel_hi:[1,0,1] neg_lo:[0,0,1] neg_hi:[0,0,1]
	v_pk_fma_f32 v[246:247], v[56:57], s[12:13], v[246:247] op_sel_hi:[1,0,1]
	v_pk_fma_f32 v[56:57], v[56:57], s[76:77], v[246:247] op_sel_hi:[1,0,1]
	s_mov_b64 s[4:5], 0
	global_store_dwordx4 v[78:79], v[50:53], off nt
	global_store_dwordx4 v[78:79], v[54:57], off offset:16 nt

.LBB0_901:
	s_nop 1
	v_mad_i64_i32 v[50:51], s[0:1], v66, s33, 0
	v_lshl_add_u64 v[66:67], v[50:51], 0, v[124:125]
	s_cmp_gt_i32 s71, 8
	s_mov_b64 s[0:1], -1
	s_cbranch_scc1 .LBB0_907
	s_cmp_lt_u32 s73, 5
	s_cselect_b64 s[0:1], -1, 0
	s_cmp_gt_u32 s73, 4
	s_cbranch_scc0 .LBB0_907
	s_andn2_b64 vcc, exec, s[28:29]
	s_mov_b64 s[4:5], -1
	s_cbranch_vccnz .LBB0_905
	s_mov_b32 s4, 0x3fb8aa3b
	s_mov_b32 s76, 0x3f317217
	s_mov_b32 s12, 0x3377d1cf
	v_lshl_add_u64 v[68:69], v[66:67], 2, s[86:87]
	v_pk_mul_f32 v[50:51], v[64:65], s[4:5] op_sel_hi:[1,0]
	v_pk_mul_f32 v[52:53], v[62:63], s[4:5] op_sel_hi:[1,0]
	v_pk_mul_f32 v[54:55], v[60:61], s[4:5] op_sel_hi:[1,0]
	v_pk_mul_f32 v[56:57], v[58:59], s[4:5] op_sel_hi:[1,0]
	v_exp_f32_e32 v50, v50
	v_exp_f32_e32 v51, v51
	v_exp_f32_e32 v52, v52
	v_exp_f32_e32 v53, v53
	v_exp_f32_e32 v54, v54
	v_exp_f32_e32 v55, v55
	v_exp_f32_e32 v56, v56
	v_exp_f32_e32 v57, v57
	v_pk_add_f32 v[50:51], v[50:51], 1.0 op_sel_hi:[1,0]
	v_pk_add_f32 v[52:53], v[52:53], 1.0 op_sel_hi:[1,0]
	v_pk_add_f32 v[54:55], v[54:55], 1.0 op_sel_hi:[1,0]
	v_pk_add_f32 v[56:57], v[56:57], 1.0 op_sel_hi:[1,0]
	v_rcp_f32_e32 v50, v50
	v_rcp_f32_e32 v51, v51
	v_rcp_f32_e32 v52, v52
	v_rcp_f32_e32 v53, v53
	v_rcp_f32_e32 v54, v54
	v_rcp_f32_e32 v55, v55
	v_rcp_f32_e32 v56, v56
	v_rcp_f32_e32 v57, v57
	v_pk_mul_f32 v[50:51], v[50:51], v[228:229]
	v_pk_mul_f32 v[52:53], v[52:53], v[230:231]
	v_pk_mul_f32 v[54:55], v[54:55], v[232:233]
	v_pk_mul_f32 v[56:57], v[56:57], v[234:235]
	v_min_f32_e32 v50, 0x3f7fffef, v50
	v_min_f32_e32 v51, 0x3f7fffef, v51
	v_min_f32_e32 v52, 0x3f7fffef, v52
	v_min_f32_e32 v53, 0x3f7fffef, v53
	v_min_f32_e32 v54, 0x3f7fffef, v54
	v_min_f32_e32 v55, 0x3f7fffef, v55
	v_min_f32_e32 v56, 0x3f7fffef, v56
	v_min_f32_e32 v57, 0x3f7fffef, v57
	v_pk_add_f32 v[50:51], v[50:51], 1.0 op_sel_hi:[1,0] neg_lo:[1,0] neg_hi:[1,0]
	v_pk_add_f32 v[52:53], v[52:53], 1.0 op_sel_hi:[1,0] neg_lo:[1,0] neg_hi:[1,0]
	v_pk_add_f32 v[54:55], v[54:55], 1.0 op_sel_hi:[1,0] neg_lo:[1,0] neg_hi:[1,0]
	v_pk_add_f32 v[56:57], v[56:57], 1.0 op_sel_hi:[1,0] neg_lo:[1,0] neg_hi:[1,0]
	v_log_f32_e32 v50, v50
	v_log_f32_e32 v51, v51
	v_log_f32_e32 v52, v52
	v_log_f32_e32 v53, v53
	v_log_f32_e32 v54, v54
	v_log_f32_e32 v55, v55
	v_log_f32_e32 v56, v56
	v_log_f32_e32 v57, v57
	v_pk_mul_f32 v[244:245], v[50:51], s[76:77] op_sel_hi:[1,0]
	v_pk_fma_f32 v[244:245], v[50:51], s[76:77], v[244:245] op_sel_hi:[1,0,1] neg_lo:[0,0,1] neg_hi:[0,0,1]
	v_pk_fma_f32 v[244:245], v[50:51], s[12:13], v[244:245] op_sel_hi:[1,0,1]
	v_pk_fma_f32 v[50:51], v[50:51], s[76:77], v[244:245] op_sel_hi:[1,0,1]
	v_pk_mul_f32 v[246:247], v[52:53], s[76:77] op_sel_hi:[1,0]
	v_pk_fma_f32 v[246:247], v[52:53], s[76:77], v[246:247] op_sel_hi:[1,0,1] neg_lo:[0,0,1] neg_hi:[0,0,1]
	v_pk_fma_f32 v[246:247], v[52:53], s[12:13], v[246:247] op_sel_hi:[1,0,1]
	v_pk_fma_f32 v[52:53], v[52:53], s[76:77], v[246:247] op_sel_hi:[1,0,1]
	v_pk_mul_f32 v[244:245], v[54:55], s[76:77] op_sel_hi:[1,0]
	v_pk_fma_f32 v[244:245], v[54:55], s[76:77], v[244:245] op_sel_hi:[1,0,1] neg_lo:[0,0,1] neg_hi:[0,0,1]
	v_pk_fma_f32 v[244:245], v[54:55], s[12:13], v[244:245] op_sel_hi:[1,0,1]
	v_pk_fma_f32 v[54:55], v[54:55], s[76:77], v[244:245] op_sel_hi:[1,0,1]
	v_pk_mul_f32 v[246:247], v[56:57], s[76:77] op_sel_hi:[1,0]
	v_pk_fma_f32 v[246:247], v[56:57], s[76:77], v[246:247] op_sel_hi:[1,0,1] neg_lo:[0,0,1] neg_hi:[0,0,1]
	v_pk_fma_f32 v[246:247], v[56:57], s[12:13], v[246:247] op_sel_hi:[1,0,1]
	v_pk_fma_f32 v[56:57], v[56:57], s[76:77], v[246:247] op_sel_hi:[1,0,1]
	s_mov_b64 s[4:5], 0
	global_store_dwordx4 v[68:69], v[50:53], off nt
	global_store_dwordx4 v[68:69], v[54:57], off offset:16 nt

.LBB0_911:
	s_andn2_b64 vcc, exec, s[0:1]
	s_cbranch_vccnz .LBB0_928
	v_mad_i64_i32 v[60:61], s[0:1], v50, s33, v[122:123]
	s_cmp_gt_i32 s71, 8
	s_mov_b64 s[0:1], -1
	s_cbranch_scc1 .LBB0_918
	s_cmp_lt_u32 s73, 5
	s_cselect_b64 s[0:1], -1, 0
	s_cmp_gt_u32 s73, 4
	s_cbranch_scc0 .LBB0_918
	s_andn2_b64 vcc, exec, s[28:29]
	s_mov_b64 s[4:5], -1
	s_cbranch_vccnz .LBB0_916
	s_mov_b32 s4, 0x3fb8aa3b
	s_mov_b32 s76, 0x3f317217
	s_mov_b32 s12, 0x3377d1cf
	v_lshl_add_u64 v[62:63], v[60:61], 2, s[86:87]
	v_pk_mul_f32 v[34:35], v[58:59], s[4:5] op_sel_hi:[1,0]
	v_pk_mul_f32 v[36:37], v[56:57], s[4:5] op_sel_hi:[1,0]
	v_pk_mul_f32 v[38:39], v[54:55], s[4:5] op_sel_hi:[1,0]
	v_pk_mul_f32 v[40:41], v[52:53], s[4:5] op_sel_hi:[1,0]
	v_exp_f32_e32 v34, v34
	v_exp_f32_e32 v35, v35
	v_exp_f32_e32 v36, v36
	v_exp_f32_e32 v37, v37
	v_exp_f32_e32 v38, v38
	v_exp_f32_e32 v39, v39
	v_exp_f32_e32 v40, v40
	v_exp_f32_e32 v41, v41
	v_pk_add_f32 v[34:35], v[34:35], 1.0 op_sel_hi:[1,0]
	v_pk_add_f32 v[36:37], v[36:37], 1.0 op_sel_hi:[1,0]
	v_pk_add_f32 v[38:39], v[38:39], 1.0 op_sel_hi:[1,0]
	v_pk_add_f32 v[40:41], v[40:41], 1.0 op_sel_hi:[1,0]
	v_rcp_f32_e32 v34, v34
	v_rcp_f32_e32 v35, v35
	v_rcp_f32_e32 v36, v36
	v_rcp_f32_e32 v37, v37
	v_rcp_f32_e32 v38, v38
	v_rcp_f32_e32 v39, v39
	v_rcp_f32_e32 v40, v40
	v_rcp_f32_e32 v41, v41
	v_pk_mul_f32 v[34:35], v[34:35], v[220:221]
	v_pk_mul_f32 v[36:37], v[36:37], v[222:223]
	v_pk_mul_f32 v[38:39], v[38:39], v[224:225]
	v_pk_mul_f32 v[40:41], v[40:41], v[226:227]
	v_min_f32_e32 v34, 0x3f7fffef, v34
	v_min_f32_e32 v35, 0x3f7fffef, v35
	v_min_f32_e32 v36, 0x3f7fffef, v36
	v_min_f32_e32 v37, 0x3f7fffef, v37
	v_min_f32_e32 v38, 0x3f7fffef, v38
	v_min_f32_e32 v39, 0x3f7fffef, v39
	v_min_f32_e32 v40, 0x3f7fffef, v40
	v_min_f32_e32 v41, 0x3f7fffef, v41
	v_pk_add_f32 v[34:35], v[34:35], 1.0 op_sel_hi:[1,0] neg_lo:[1,0] neg_hi:[1,0]
	v_pk_add_f32 v[36:37], v[36:37], 1.0 op_sel_hi:[1,0] neg_lo:[1,0] neg_hi:[1,0]
	v_pk_add_f32 v[38:39], v[38:39], 1.0 op_sel_hi:[1,0] neg_lo:[1,0] neg_hi:[1,0]
	v_pk_add_f32 v[40:41], v[40:41], 1.0 op_sel_hi:[1,0] neg_lo:[1,0] neg_hi:[1,0]
	v_log_f32_e32 v34, v34
	v_log_f32_e32 v35, v35
	v_log_f32_e32 v36, v36
	v_log_f32_e32 v37, v37
	v_log_f32_e32 v38, v38
	v_log_f32_e32 v39, v39
	v_log_f32_e32 v40, v40
	v_log_f32_e32 v41, v41
	v_pk_mul_f32 v[244:245], v[34:35], s[76:77] op_sel_hi:[1,0]
	v_pk_fma_f32 v[244:245], v[34:35], s[76:77], v[244:245] op_sel_hi:[1,0,1] neg_lo:[0,0,1] neg_hi:[0,0,1]
	v_pk_fma_f32 v[244:245], v[34:35], s[12:13], v[244:245] op_sel_hi:[1,0,1]
	v_pk_fma_f32 v[34:35], v[34:35], s[76:77], v[244:245] op_sel_hi:[1,0,1]
	v_pk_mul_f32 v[246:247], v[36:37], s[76:77] op_sel_hi:[1,0]
	v_pk_fma_f32 v[246:247], v[36:37], s[76:77], v[246:247] op_sel_hi:[1,0,1] neg_lo:[0,0,1] neg_hi:[0,0,1]
	v_pk_fma_f32 v[246:247], v[36:37], s[12:13], v[246:247] op_sel_hi:[1,0,1]
	v_pk_fma_f32 v[36:37], v[36:37], s[76:77], v[246:247] op_sel_hi:[1,0,1]
	v_pk_mul_f32 v[244:245], v[38:39], s[76:77] op_sel_hi:[1,0]
	v_pk_fma_f32 v[244:245], v[38:39], s[76:77], v[244:245] op_sel_hi:[1,0,1] neg_lo:[0,0,1] neg_hi:[0,0,1]
	v_pk_fma_f32 v[244:245], v[38:39], s[12:13], v[244:245] op_sel_hi:[1,0,1]
	v_pk_fma_f32 v[38:39], v[38:39], s[76:77], v[244:245] op_sel_hi:[1,0,1]
	v_pk_mul_f32 v[246:247], v[40:41], s[76:77] op_sel_hi:[1,0]
	v_pk_fma_f32 v[246:247], v[40:41], s[76:77], v[246:247] op_sel_hi:[1,0,1] neg_lo:[0,0,1] neg_hi:[0,0,1]
	v_pk_fma_f32 v[246:247], v[40:41], s[12:13], v[246:247] op_sel_hi:[1,0,1]
	v_pk_fma_f32 v[40:41], v[40:41], s[76:77], v[246:247] op_sel_hi:[1,0,1]
	s_mov_b64 s[4:5], 0
	global_store_dwordx4 v[62:63], v[34:37], off nt
	global_store_dwordx4 v[62:63], v[38:41], off offset:16 nt

.LBB0_920:
	s_nop 1
	v_mad_i64_i32 v[34:35], s[0:1], v50, s33, 0
	v_lshl_add_u64 v[50:51], v[34:35], 0, v[124:125]
	s_cmp_gt_i32 s71, 8
	s_mov_b64 s[0:1], -1
	s_cbranch_scc1 .LBB0_926
	s_cmp_lt_u32 s73, 5
	s_cselect_b64 s[0:1], -1, 0
	s_cmp_gt_u32 s73, 4
	s_cbranch_scc0 .LBB0_926
	s_andn2_b64 vcc, exec, s[28:29]
	s_mov_b64 s[4:5], -1
	s_cbranch_vccnz .LBB0_924
	s_mov_b32 s4, 0x3fb8aa3b
	s_mov_b32 s76, 0x3f317217
	s_mov_b32 s12, 0x3377d1cf
	v_lshl_add_u64 v[52:53], v[50:51], 2, s[86:87]
	v_pk_mul_f32 v[34:35], v[48:49], s[4:5] op_sel_hi:[1,0]
	v_pk_mul_f32 v[36:37], v[46:47], s[4:5] op_sel_hi:[1,0]
	v_pk_mul_f32 v[38:39], v[44:45], s[4:5] op_sel_hi:[1,0]
	v_pk_mul_f32 v[40:41], v[42:43], s[4:5] op_sel_hi:[1,0]
	v_exp_f32_e32 v34, v34
	v_exp_f32_e32 v35, v35
	v_exp_f32_e32 v36, v36
	v_exp_f32_e32 v37, v37
	v_exp_f32_e32 v38, v38
	v_exp_f32_e32 v39, v39
	v_exp_f32_e32 v40, v40
	v_exp_f32_e32 v41, v41
	v_pk_add_f32 v[34:35], v[34:35], 1.0 op_sel_hi:[1,0]
	v_pk_add_f32 v[36:37], v[36:37], 1.0 op_sel_hi:[1,0]
	v_pk_add_f32 v[38:39], v[38:39], 1.0 op_sel_hi:[1,0]
	v_pk_add_f32 v[40:41], v[40:41], 1.0 op_sel_hi:[1,0]
	v_rcp_f32_e32 v34, v34
	v_rcp_f32_e32 v35, v35
	v_rcp_f32_e32 v36, v36
	v_rcp_f32_e32 v37, v37
	v_rcp_f32_e32 v38, v38
	v_rcp_f32_e32 v39, v39
	v_rcp_f32_e32 v40, v40
	v_rcp_f32_e32 v41, v41
	v_pk_mul_f32 v[34:35], v[34:35], v[228:229]
	v_pk_mul_f32 v[36:37], v[36:37], v[230:231]
	v_pk_mul_f32 v[38:39], v[38:39], v[232:233]
	v_pk_mul_f32 v[40:41], v[40:41], v[234:235]
	v_min_f32_e32 v34, 0x3f7fffef, v34
	v_min_f32_e32 v35, 0x3f7fffef, v35
	v_min_f32_e32 v36, 0x3f7fffef, v36
	v_min_f32_e32 v37, 0x3f7fffef, v37
	v_min_f32_e32 v38, 0x3f7fffef, v38
	v_min_f32_e32 v39, 0x3f7fffef, v39
	v_min_f32_e32 v40, 0x3f7fffef, v40
	v_min_f32_e32 v41, 0x3f7fffef, v41
	v_pk_add_f32 v[34:35], v[34:35], 1.0 op_sel_hi:[1,0] neg_lo:[1,0] neg_hi:[1,0]
	v_pk_add_f32 v[36:37], v[36:37], 1.0 op_sel_hi:[1,0] neg_lo:[1,0] neg_hi:[1,0]
	v_pk_add_f32 v[38:39], v[38:39], 1.0 op_sel_hi:[1,0] neg_lo:[1,0] neg_hi:[1,0]
	v_pk_add_f32 v[40:41], v[40:41], 1.0 op_sel_hi:[1,0] neg_lo:[1,0] neg_hi:[1,0]
	v_log_f32_e32 v34, v34
	v_log_f32_e32 v35, v35
	v_log_f32_e32 v36, v36
	v_log_f32_e32 v37, v37
	v_log_f32_e32 v38, v38
	v_log_f32_e32 v39, v39
	v_log_f32_e32 v40, v40
	v_log_f32_e32 v41, v41
	v_pk_mul_f32 v[244:245], v[34:35], s[76:77] op_sel_hi:[1,0]
	v_pk_fma_f32 v[244:245], v[34:35], s[76:77], v[244:245] op_sel_hi:[1,0,1] neg_lo:[0,0,1] neg_hi:[0,0,1]
	v_pk_fma_f32 v[244:245], v[34:35], s[12:13], v[244:245] op_sel_hi:[1,0,1]
	v_pk_fma_f32 v[34:35], v[34:35], s[76:77], v[244:245] op_sel_hi:[1,0,1]
	v_pk_mul_f32 v[246:247], v[36:37], s[76:77] op_sel_hi:[1,0]
	v_pk_fma_f32 v[246:247], v[36:37], s[76:77], v[246:247] op_sel_hi:[1,0,1] neg_lo:[0,0,1] neg_hi:[0,0,1]
	v_pk_fma_f32 v[246:247], v[36:37], s[12:13], v[246:247] op_sel_hi:[1,0,1]
	v_pk_fma_f32 v[36:37], v[36:37], s[76:77], v[246:247] op_sel_hi:[1,0,1]
	v_pk_mul_f32 v[244:245], v[38:39], s[76:77] op_sel_hi:[1,0]
	v_pk_fma_f32 v[244:245], v[38:39], s[76:77], v[244:245] op_sel_hi:[1,0,1] neg_lo:[0,0,1] neg_hi:[0,0,1]
	v_pk_fma_f32 v[244:245], v[38:39], s[12:13], v[244:245] op_sel_hi:[1,0,1]
	v_pk_fma_f32 v[38:39], v[38:39], s[76:77], v[244:245] op_sel_hi:[1,0,1]
	v_pk_mul_f32 v[246:247], v[40:41], s[76:77] op_sel_hi:[1,0]
	v_pk_fma_f32 v[246:247], v[40:41], s[76:77], v[246:247] op_sel_hi:[1,0,1] neg_lo:[0,0,1] neg_hi:[0,0,1]
	v_pk_fma_f32 v[246:247], v[40:41], s[12:13], v[246:247] op_sel_hi:[1,0,1]
	v_pk_fma_f32 v[40:41], v[40:41], s[76:77], v[246:247] op_sel_hi:[1,0,1]
	s_mov_b64 s[4:5], 0
	global_store_dwordx4 v[52:53], v[34:37], off nt
	global_store_dwordx4 v[52:53], v[38:41], off offset:16 nt

.LBB0_930:
	s_andn2_b64 vcc, exec, s[0:1]
	s_cbranch_vccnz .LBB0_947
	v_mad_i64_i32 v[44:45], s[0:1], v34, s33, v[122:123]
	s_cmp_gt_i32 s71, 8
	s_mov_b64 s[0:1], -1
	s_cbranch_scc1 .LBB0_937
	s_cmp_lt_u32 s73, 5
	s_cselect_b64 s[0:1], -1, 0
	s_cmp_gt_u32 s73, 4
	s_cbranch_scc0 .LBB0_937
	s_andn2_b64 vcc, exec, s[28:29]
	s_mov_b64 s[4:5], -1
	s_cbranch_vccnz .LBB0_935
	s_mov_b32 s4, 0x3fb8aa3b
	s_mov_b32 s76, 0x3f317217
	s_mov_b32 s12, 0x3377d1cf
	v_lshl_add_u64 v[46:47], v[44:45], 2, s[86:87]
	v_pk_mul_f32 v[18:19], v[42:43], s[4:5] op_sel_hi:[1,0]
	v_pk_mul_f32 v[20:21], v[40:41], s[4:5] op_sel_hi:[1,0]
	v_pk_mul_f32 v[22:23], v[38:39], s[4:5] op_sel_hi:[1,0]
	v_pk_mul_f32 v[24:25], v[36:37], s[4:5] op_sel_hi:[1,0]
	v_exp_f32_e32 v18, v18
	v_exp_f32_e32 v19, v19
	v_exp_f32_e32 v20, v20
	v_exp_f32_e32 v21, v21
	v_exp_f32_e32 v22, v22
	v_exp_f32_e32 v23, v23
	v_exp_f32_e32 v24, v24
	v_exp_f32_e32 v25, v25
	v_pk_add_f32 v[18:19], v[18:19], 1.0 op_sel_hi:[1,0]
	v_pk_add_f32 v[20:21], v[20:21], 1.0 op_sel_hi:[1,0]
	v_pk_add_f32 v[22:23], v[22:23], 1.0 op_sel_hi:[1,0]
	v_pk_add_f32 v[24:25], v[24:25], 1.0 op_sel_hi:[1,0]
	v_rcp_f32_e32 v18, v18
	v_rcp_f32_e32 v19, v19
	v_rcp_f32_e32 v20, v20
	v_rcp_f32_e32 v21, v21
	v_rcp_f32_e32 v22, v22
	v_rcp_f32_e32 v23, v23
	v_rcp_f32_e32 v24, v24
	v_rcp_f32_e32 v25, v25
	v_pk_mul_f32 v[18:19], v[18:19], v[220:221]
	v_pk_mul_f32 v[20:21], v[20:21], v[222:223]
	v_pk_mul_f32 v[22:23], v[22:23], v[224:225]
	v_pk_mul_f32 v[24:25], v[24:25], v[226:227]
	v_min_f32_e32 v18, 0x3f7fffef, v18
	v_min_f32_e32 v19, 0x3f7fffef, v19
	v_min_f32_e32 v20, 0x3f7fffef, v20
	v_min_f32_e32 v21, 0x3f7fffef, v21
	v_min_f32_e32 v22, 0x3f7fffef, v22
	v_min_f32_e32 v23, 0x3f7fffef, v23
	v_min_f32_e32 v24, 0x3f7fffef, v24
	v_min_f32_e32 v25, 0x3f7fffef, v25
	v_pk_add_f32 v[18:19], v[18:19], 1.0 op_sel_hi:[1,0] neg_lo:[1,0] neg_hi:[1,0]
	v_pk_add_f32 v[20:21], v[20:21], 1.0 op_sel_hi:[1,0] neg_lo:[1,0] neg_hi:[1,0]
	v_pk_add_f32 v[22:23], v[22:23], 1.0 op_sel_hi:[1,0] neg_lo:[1,0] neg_hi:[1,0]
	v_pk_add_f32 v[24:25], v[24:25], 1.0 op_sel_hi:[1,0] neg_lo:[1,0] neg_hi:[1,0]
	v_log_f32_e32 v18, v18
	v_log_f32_e32 v19, v19
	v_log_f32_e32 v20, v20
	v_log_f32_e32 v21, v21
	v_log_f32_e32 v22, v22
	v_log_f32_e32 v23, v23
	v_log_f32_e32 v24, v24
	v_log_f32_e32 v25, v25
	v_pk_mul_f32 v[244:245], v[18:19], s[76:77] op_sel_hi:[1,0]
	v_pk_fma_f32 v[244:245], v[18:19], s[76:77], v[244:245] op_sel_hi:[1,0,1] neg_lo:[0,0,1] neg_hi:[0,0,1]
	v_pk_fma_f32 v[244:245], v[18:19], s[12:13], v[244:245] op_sel_hi:[1,0,1]
	v_pk_fma_f32 v[18:19], v[18:19], s[76:77], v[244:245] op_sel_hi:[1,0,1]
	v_pk_mul_f32 v[246:247], v[20:21], s[76:77] op_sel_hi:[1,0]
	v_pk_fma_f32 v[246:247], v[20:21], s[76:77], v[246:247] op_sel_hi:[1,0,1] neg_lo:[0,0,1] neg_hi:[0,0,1]
	v_pk_fma_f32 v[246:247], v[20:21], s[12:13], v[246:247] op_sel_hi:[1,0,1]
	v_pk_fma_f32 v[20:21], v[20:21], s[76:77], v[246:247] op_sel_hi:[1,0,1]
	v_pk_mul_f32 v[244:245], v[22:23], s[76:77] op_sel_hi:[1,0]
	v_pk_fma_f32 v[244:245], v[22:23], s[76:77], v[244:245] op_sel_hi:[1,0,1] neg_lo:[0,0,1] neg_hi:[0,0,1]
	v_pk_fma_f32 v[244:245], v[22:23], s[12:13], v[244:245] op_sel_hi:[1,0,1]
	v_pk_fma_f32 v[22:23], v[22:23], s[76:77], v[244:245] op_sel_hi:[1,0,1]
	v_pk_mul_f32 v[246:247], v[24:25], s[76:77] op_sel_hi:[1,0]
	v_pk_fma_f32 v[246:247], v[24:25], s[76:77], v[246:247] op_sel_hi:[1,0,1] neg_lo:[0,0,1] neg_hi:[0,0,1]
	v_pk_fma_f32 v[246:247], v[24:25], s[12:13], v[246:247] op_sel_hi:[1,0,1]
	v_pk_fma_f32 v[24:25], v[24:25], s[76:77], v[246:247] op_sel_hi:[1,0,1]
	s_mov_b64 s[4:5], 0
	global_store_dwordx4 v[46:47], v[18:21], off nt
	global_store_dwordx4 v[46:47], v[22:25], off offset:16 nt

.LBB0_939:
	s_nop 1
	v_mad_i64_i32 v[18:19], s[0:1], v34, s33, 0
	v_lshl_add_u64 v[34:35], v[18:19], 0, v[124:125]
	s_cmp_gt_i32 s71, 8
	s_mov_b64 s[0:1], -1
	s_cbranch_scc1 .LBB0_945
	s_cmp_lt_u32 s73, 5
	s_cselect_b64 s[0:1], -1, 0
	s_cmp_gt_u32 s73, 4
	s_cbranch_scc0 .LBB0_945
	s_andn2_b64 vcc, exec, s[28:29]
	s_mov_b64 s[4:5], -1
	s_cbranch_vccnz .LBB0_943
	s_mov_b32 s4, 0x3fb8aa3b
	s_mov_b32 s76, 0x3f317217
	s_mov_b32 s12, 0x3377d1cf
	v_lshl_add_u64 v[36:37], v[34:35], 2, s[86:87]
	v_pk_mul_f32 v[18:19], v[32:33], s[4:5] op_sel_hi:[1,0]
	v_pk_mul_f32 v[20:21], v[30:31], s[4:5] op_sel_hi:[1,0]
	v_pk_mul_f32 v[22:23], v[28:29], s[4:5] op_sel_hi:[1,0]
	v_pk_mul_f32 v[24:25], v[26:27], s[4:5] op_sel_hi:[1,0]
	v_exp_f32_e32 v18, v18
	v_exp_f32_e32 v19, v19
	v_exp_f32_e32 v20, v20
	v_exp_f32_e32 v21, v21
	v_exp_f32_e32 v22, v22
	v_exp_f32_e32 v23, v23
	v_exp_f32_e32 v24, v24
	v_exp_f32_e32 v25, v25
	v_pk_add_f32 v[18:19], v[18:19], 1.0 op_sel_hi:[1,0]
	v_pk_add_f32 v[20:21], v[20:21], 1.0 op_sel_hi:[1,0]
	v_pk_add_f32 v[22:23], v[22:23], 1.0 op_sel_hi:[1,0]
	v_pk_add_f32 v[24:25], v[24:25], 1.0 op_sel_hi:[1,0]
	v_rcp_f32_e32 v18, v18
	v_rcp_f32_e32 v19, v19
	v_rcp_f32_e32 v20, v20
	v_rcp_f32_e32 v21, v21
	v_rcp_f32_e32 v22, v22
	v_rcp_f32_e32 v23, v23
	v_rcp_f32_e32 v24, v24
	v_rcp_f32_e32 v25, v25
	v_pk_mul_f32 v[18:19], v[18:19], v[228:229]
	v_pk_mul_f32 v[20:21], v[20:21], v[230:231]
	v_pk_mul_f32 v[22:23], v[22:23], v[232:233]
	v_pk_mul_f32 v[24:25], v[24:25], v[234:235]
	v_min_f32_e32 v18, 0x3f7fffef, v18
	v_min_f32_e32 v19, 0x3f7fffef, v19
	v_min_f32_e32 v20, 0x3f7fffef, v20
	v_min_f32_e32 v21, 0x3f7fffef, v21
	v_min_f32_e32 v22, 0x3f7fffef, v22
	v_min_f32_e32 v23, 0x3f7fffef, v23
	v_min_f32_e32 v24, 0x3f7fffef, v24
	v_min_f32_e32 v25, 0x3f7fffef, v25
	v_pk_add_f32 v[18:19], v[18:19], 1.0 op_sel_hi:[1,0] neg_lo:[1,0] neg_hi:[1,0]
	v_pk_add_f32 v[20:21], v[20:21], 1.0 op_sel_hi:[1,0] neg_lo:[1,0] neg_hi:[1,0]
	v_pk_add_f32 v[22:23], v[22:23], 1.0 op_sel_hi:[1,0] neg_lo:[1,0] neg_hi:[1,0]
	v_pk_add_f32 v[24:25], v[24:25], 1.0 op_sel_hi:[1,0] neg_lo:[1,0] neg_hi:[1,0]
	v_log_f32_e32 v18, v18
	v_log_f32_e32 v19, v19
	v_log_f32_e32 v20, v20
	v_log_f32_e32 v21, v21
	v_log_f32_e32 v22, v22
	v_log_f32_e32 v23, v23
	v_log_f32_e32 v24, v24
	v_log_f32_e32 v25, v25
	v_pk_mul_f32 v[244:245], v[18:19], s[76:77] op_sel_hi:[1,0]
	v_pk_fma_f32 v[244:245], v[18:19], s[76:77], v[244:245] op_sel_hi:[1,0,1] neg_lo:[0,0,1] neg_hi:[0,0,1]
	v_pk_fma_f32 v[244:245], v[18:19], s[12:13], v[244:245] op_sel_hi:[1,0,1]
	v_pk_fma_f32 v[18:19], v[18:19], s[76:77], v[244:245] op_sel_hi:[1,0,1]
	v_pk_mul_f32 v[246:247], v[20:21], s[76:77] op_sel_hi:[1,0]
	v_pk_fma_f32 v[246:247], v[20:21], s[76:77], v[246:247] op_sel_hi:[1,0,1] neg_lo:[0,0,1] neg_hi:[0,0,1]
	v_pk_fma_f32 v[246:247], v[20:21], s[12:13], v[246:247] op_sel_hi:[1,0,1]
	v_pk_fma_f32 v[20:21], v[20:21], s[76:77], v[246:247] op_sel_hi:[1,0,1]
	v_pk_mul_f32 v[244:245], v[22:23], s[76:77] op_sel_hi:[1,0]
	v_pk_fma_f32 v[244:245], v[22:23], s[76:77], v[244:245] op_sel_hi:[1,0,1] neg_lo:[0,0,1] neg_hi:[0,0,1]
	v_pk_fma_f32 v[244:245], v[22:23], s[12:13], v[244:245] op_sel_hi:[1,0,1]
	v_pk_fma_f32 v[22:23], v[22:23], s[76:77], v[244:245] op_sel_hi:[1,0,1]
	v_pk_mul_f32 v[246:247], v[24:25], s[76:77] op_sel_hi:[1,0]
	v_pk_fma_f32 v[246:247], v[24:25], s[76:77], v[246:247] op_sel_hi:[1,0,1] neg_lo:[0,0,1] neg_hi:[0,0,1]
	v_pk_fma_f32 v[246:247], v[24:25], s[12:13], v[246:247] op_sel_hi:[1,0,1]
	v_pk_fma_f32 v[24:25], v[24:25], s[76:77], v[246:247] op_sel_hi:[1,0,1]
	s_mov_b64 s[4:5], 0
	global_store_dwordx4 v[36:37], v[18:21], off nt
	global_store_dwordx4 v[36:37], v[22:25], off offset:16 nt

.LBB0_949:
	s_andn2_b64 vcc, exec, s[0:1]
	s_cbranch_vccnz .LBB0_794
	v_mad_i64_i32 v[28:29], s[0:1], v18, s33, v[122:123]
	s_cmp_gt_i32 s71, 8
	s_mov_b64 s[0:1], -1
	s_cbranch_scc1 .LBB0_956
	s_cmp_lt_u32 s73, 5
	s_cselect_b64 s[0:1], -1, 0
	s_cmp_gt_u32 s73, 4
	s_cbranch_scc0 .LBB0_956
	s_andn2_b64 vcc, exec, s[28:29]
	s_mov_b64 s[4:5], -1
	s_cbranch_vccnz .LBB0_954
	s_mov_b32 s4, 0x3fb8aa3b
	s_mov_b32 s12, 0x3f317217
	s_mov_b32 s10, 0x3377d1cf
	v_lshl_add_u64 v[30:31], v[28:29], 2, s[86:87]
	v_pk_mul_f32 v[2:3], v[26:27], s[4:5] op_sel_hi:[1,0]
	v_pk_mul_f32 v[4:5], v[24:25], s[4:5] op_sel_hi:[1,0]
	v_pk_mul_f32 v[6:7], v[22:23], s[4:5] op_sel_hi:[1,0]
	v_pk_mul_f32 v[8:9], v[20:21], s[4:5] op_sel_hi:[1,0]
	v_exp_f32_e32 v2, v2
	v_exp_f32_e32 v3, v3
	v_exp_f32_e32 v4, v4
	v_exp_f32_e32 v5, v5
	v_exp_f32_e32 v6, v6
	v_exp_f32_e32 v7, v7
	v_exp_f32_e32 v8, v8
	v_exp_f32_e32 v9, v9
	v_pk_add_f32 v[2:3], v[2:3], 1.0 op_sel_hi:[1,0]
	v_pk_add_f32 v[4:5], v[4:5], 1.0 op_sel_hi:[1,0]
	v_pk_add_f32 v[6:7], v[6:7], 1.0 op_sel_hi:[1,0]
	v_pk_add_f32 v[8:9], v[8:9], 1.0 op_sel_hi:[1,0]
	v_rcp_f32_e32 v2, v2
	v_rcp_f32_e32 v3, v3
	v_rcp_f32_e32 v4, v4
	v_rcp_f32_e32 v5, v5
	v_rcp_f32_e32 v6, v6
	v_rcp_f32_e32 v7, v7
	v_rcp_f32_e32 v8, v8
	v_rcp_f32_e32 v9, v9
	v_pk_mul_f32 v[2:3], v[2:3], v[220:221]
	v_pk_mul_f32 v[4:5], v[4:5], v[222:223]
	v_pk_mul_f32 v[6:7], v[6:7], v[224:225]
	v_pk_mul_f32 v[8:9], v[8:9], v[226:227]
	v_min_f32_e32 v2, 0x3f7fffef, v2
	v_min_f32_e32 v3, 0x3f7fffef, v3
	v_min_f32_e32 v4, 0x3f7fffef, v4
	v_min_f32_e32 v5, 0x3f7fffef, v5
	v_min_f32_e32 v6, 0x3f7fffef, v6
	v_min_f32_e32 v7, 0x3f7fffef, v7
	v_min_f32_e32 v8, 0x3f7fffef, v8
	v_min_f32_e32 v9, 0x3f7fffef, v9
	v_pk_add_f32 v[2:3], v[2:3], 1.0 op_sel_hi:[1,0] neg_lo:[1,0] neg_hi:[1,0]
	v_pk_add_f32 v[4:5], v[4:5], 1.0 op_sel_hi:[1,0] neg_lo:[1,0] neg_hi:[1,0]
	v_pk_add_f32 v[6:7], v[6:7], 1.0 op_sel_hi:[1,0] neg_lo:[1,0] neg_hi:[1,0]
	v_pk_add_f32 v[8:9], v[8:9], 1.0 op_sel_hi:[1,0] neg_lo:[1,0] neg_hi:[1,0]
	v_log_f32_e32 v2, v2
	v_log_f32_e32 v3, v3
	v_log_f32_e32 v4, v4
	v_log_f32_e32 v5, v5
	v_log_f32_e32 v6, v6
	v_log_f32_e32 v7, v7
	v_log_f32_e32 v8, v8
	v_log_f32_e32 v9, v9
	v_pk_mul_f32 v[244:245], v[2:3], s[12:13] op_sel_hi:[1,0]
	v_pk_fma_f32 v[244:245], v[2:3], s[12:13], v[244:245] op_sel_hi:[1,0,1] neg_lo:[0,0,1] neg_hi:[0,0,1]
	v_pk_fma_f32 v[244:245], v[2:3], s[10:11], v[244:245] op_sel_hi:[1,0,1]
	v_pk_fma_f32 v[2:3], v[2:3], s[12:13], v[244:245] op_sel_hi:[1,0,1]
	v_pk_mul_f32 v[246:247], v[4:5], s[12:13] op_sel_hi:[1,0]
	v_pk_fma_f32 v[246:247], v[4:5], s[12:13], v[246:247] op_sel_hi:[1,0,1] neg_lo:[0,0,1] neg_hi:[0,0,1]
	v_pk_fma_f32 v[246:247], v[4:5], s[10:11], v[246:247] op_sel_hi:[1,0,1]
	v_pk_fma_f32 v[4:5], v[4:5], s[12:13], v[246:247] op_sel_hi:[1,0,1]
	v_pk_mul_f32 v[244:245], v[6:7], s[12:13] op_sel_hi:[1,0]
	v_pk_fma_f32 v[244:245], v[6:7], s[12:13], v[244:245] op_sel_hi:[1,0,1] neg_lo:[0,0,1] neg_hi:[0,0,1]
	v_pk_fma_f32 v[244:245], v[6:7], s[10:11], v[244:245] op_sel_hi:[1,0,1]
	v_pk_fma_f32 v[6:7], v[6:7], s[12:13], v[244:245] op_sel_hi:[1,0,1]
	v_pk_mul_f32 v[246:247], v[8:9], s[12:13] op_sel_hi:[1,0]
	v_pk_fma_f32 v[246:247], v[8:9], s[12:13], v[246:247] op_sel_hi:[1,0,1] neg_lo:[0,0,1] neg_hi:[0,0,1]
	v_pk_fma_f32 v[246:247], v[8:9], s[10:11], v[246:247] op_sel_hi:[1,0,1]
	v_pk_fma_f32 v[8:9], v[8:9], s[12:13], v[246:247] op_sel_hi:[1,0,1]
	s_mov_b64 s[4:5], 0
	global_store_dwordx4 v[30:31], v[2:5], off nt
	global_store_dwordx4 v[30:31], v[6:9], off offset:16 nt

.LBB0_958:
	s_nop 1
	v_mad_i64_i32 v[2:3], s[0:1], v18, s33, 0
	v_lshl_add_u64 v[18:19], v[2:3], 0, v[124:125]
	s_cmp_gt_i32 s71, 8
	s_mov_b64 s[0:1], -1
	s_cbranch_scc1 .LBB0_964
	s_cmp_lt_u32 s73, 5
	s_cselect_b64 s[0:1], -1, 0
	s_cmp_gt_u32 s73, 4
	s_cbranch_scc0 .LBB0_964
	s_andn2_b64 vcc, exec, s[28:29]
	s_mov_b64 s[4:5], -1
	s_cbranch_vccnz .LBB0_962
	s_mov_b32 s4, 0x3fb8aa3b
	s_mov_b32 s12, 0x3f317217
	s_mov_b32 s10, 0x3377d1cf
	v_lshl_add_u64 v[20:21], v[18:19], 2, s[86:87]
	v_pk_mul_f32 v[2:3], v[16:17], s[4:5] op_sel_hi:[1,0]
	v_pk_mul_f32 v[4:5], v[14:15], s[4:5] op_sel_hi:[1,0]
	v_pk_mul_f32 v[6:7], v[12:13], s[4:5] op_sel_hi:[1,0]
	v_pk_mul_f32 v[8:9], v[10:11], s[4:5] op_sel_hi:[1,0]
	v_exp_f32_e32 v2, v2
	v_exp_f32_e32 v3, v3
	v_exp_f32_e32 v4, v4
	v_exp_f32_e32 v5, v5
	v_exp_f32_e32 v6, v6
	v_exp_f32_e32 v7, v7
	v_exp_f32_e32 v8, v8
	v_exp_f32_e32 v9, v9
	v_pk_add_f32 v[2:3], v[2:3], 1.0 op_sel_hi:[1,0]
	v_pk_add_f32 v[4:5], v[4:5], 1.0 op_sel_hi:[1,0]
	v_pk_add_f32 v[6:7], v[6:7], 1.0 op_sel_hi:[1,0]
	v_pk_add_f32 v[8:9], v[8:9], 1.0 op_sel_hi:[1,0]
	v_rcp_f32_e32 v2, v2
	v_rcp_f32_e32 v3, v3
	v_rcp_f32_e32 v4, v4
	v_rcp_f32_e32 v5, v5
	v_rcp_f32_e32 v6, v6
	v_rcp_f32_e32 v7, v7
	v_rcp_f32_e32 v8, v8
	v_rcp_f32_e32 v9, v9
	v_pk_mul_f32 v[2:3], v[2:3], v[228:229]
	v_pk_mul_f32 v[4:5], v[4:5], v[230:231]
	v_pk_mul_f32 v[6:7], v[6:7], v[232:233]
	v_pk_mul_f32 v[8:9], v[8:9], v[234:235]
	v_min_f32_e32 v2, 0x3f7fffef, v2
	v_min_f32_e32 v3, 0x3f7fffef, v3
	v_min_f32_e32 v4, 0x3f7fffef, v4
	v_min_f32_e32 v5, 0x3f7fffef, v5
	v_min_f32_e32 v6, 0x3f7fffef, v6
	v_min_f32_e32 v7, 0x3f7fffef, v7
	v_min_f32_e32 v8, 0x3f7fffef, v8
	v_min_f32_e32 v9, 0x3f7fffef, v9
	v_pk_add_f32 v[2:3], v[2:3], 1.0 op_sel_hi:[1,0] neg_lo:[1,0] neg_hi:[1,0]
	v_pk_add_f32 v[4:5], v[4:5], 1.0 op_sel_hi:[1,0] neg_lo:[1,0] neg_hi:[1,0]
	v_pk_add_f32 v[6:7], v[6:7], 1.0 op_sel_hi:[1,0] neg_lo:[1,0] neg_hi:[1,0]
	v_pk_add_f32 v[8:9], v[8:9], 1.0 op_sel_hi:[1,0] neg_lo:[1,0] neg_hi:[1,0]
	v_log_f32_e32 v2, v2
	v_log_f32_e32 v3, v3
	v_log_f32_e32 v4, v4
	v_log_f32_e32 v5, v5
	v_log_f32_e32 v6, v6
	v_log_f32_e32 v7, v7
	v_log_f32_e32 v8, v8
	v_log_f32_e32 v9, v9
	v_pk_mul_f32 v[244:245], v[2:3], s[12:13] op_sel_hi:[1,0]
	v_pk_fma_f32 v[244:245], v[2:3], s[12:13], v[244:245] op_sel_hi:[1,0,1] neg_lo:[0,0,1] neg_hi:[0,0,1]
	v_pk_fma_f32 v[244:245], v[2:3], s[10:11], v[244:245] op_sel_hi:[1,0,1]
	v_pk_fma_f32 v[2:3], v[2:3], s[12:13], v[244:245] op_sel_hi:[1,0,1]
	v_pk_mul_f32 v[246:247], v[4:5], s[12:13] op_sel_hi:[1,0]
	v_pk_fma_f32 v[246:247], v[4:5], s[12:13], v[246:247] op_sel_hi:[1,0,1] neg_lo:[0,0,1] neg_hi:[0,0,1]
	v_pk_fma_f32 v[246:247], v[4:5], s[10:11], v[246:247] op_sel_hi:[1,0,1]
	v_pk_fma_f32 v[4:5], v[4:5], s[12:13], v[246:247] op_sel_hi:[1,0,1]
	v_pk_mul_f32 v[244:245], v[6:7], s[12:13] op_sel_hi:[1,0]
	v_pk_fma_f32 v[244:245], v[6:7], s[12:13], v[244:245] op_sel_hi:[1,0,1] neg_lo:[0,0,1] neg_hi:[0,0,1]
	v_pk_fma_f32 v[244:245], v[6:7], s[10:11], v[244:245] op_sel_hi:[1,0,1]
	v_pk_fma_f32 v[6:7], v[6:7], s[12:13], v[244:245] op_sel_hi:[1,0,1]
	v_pk_mul_f32 v[246:247], v[8:9], s[12:13] op_sel_hi:[1,0]
	v_pk_fma_f32 v[246:247], v[8:9], s[12:13], v[246:247] op_sel_hi:[1,0,1] neg_lo:[0,0,1] neg_hi:[0,0,1]
	v_pk_fma_f32 v[246:247], v[8:9], s[10:11], v[246:247] op_sel_hi:[1,0,1]
	v_pk_fma_f32 v[8:9], v[8:9], s[12:13], v[246:247] op_sel_hi:[1,0,1]
	s_mov_b64 s[4:5], 0
	global_store_dwordx4 v[20:21], v[2:5], off nt
	global_store_dwordx4 v[20:21], v[6:9], off offset:16 nt

.LBB0_966:
	s_andn2_b64 vcc, exec, s[28:29]
	s_mov_b64 s[0:1], -1
	s_cbranch_vccnz .LBB0_968
	s_mov_b32 s0, 0x3fb8aa3b
	s_mov_b32 s4, 0x3f317217
	s_mov_b32 s10, 0x3377d1cf
	v_lshl_add_u64 v[160:161], v[158:159], 2, s[86:87]
	v_pk_mul_f32 v[114:115], v[156:157], s[0:1] op_sel_hi:[1,0]
	v_pk_mul_f32 v[116:117], v[154:155], s[0:1] op_sel_hi:[1,0]
	v_pk_mul_f32 v[118:119], v[152:153], s[0:1] op_sel_hi:[1,0]
	v_pk_mul_f32 v[120:121], v[150:151], s[0:1] op_sel_hi:[1,0]
	v_exp_f32_e32 v114, v114
	v_exp_f32_e32 v115, v115
	v_exp_f32_e32 v116, v116
	v_exp_f32_e32 v117, v117
	v_exp_f32_e32 v118, v118
	v_exp_f32_e32 v119, v119
	v_exp_f32_e32 v120, v120
	v_exp_f32_e32 v121, v121
	v_pk_add_f32 v[114:115], v[114:115], 1.0 op_sel_hi:[1,0]
	v_pk_add_f32 v[116:117], v[116:117], 1.0 op_sel_hi:[1,0]
	v_pk_add_f32 v[118:119], v[118:119], 1.0 op_sel_hi:[1,0]
	v_pk_add_f32 v[120:121], v[120:121], 1.0 op_sel_hi:[1,0]
	v_rcp_f32_e32 v114, v114
	v_rcp_f32_e32 v115, v115
	v_rcp_f32_e32 v116, v116
	v_rcp_f32_e32 v117, v117
	v_rcp_f32_e32 v118, v118
	v_rcp_f32_e32 v119, v119
	v_rcp_f32_e32 v120, v120
	v_rcp_f32_e32 v121, v121
	v_pk_mul_f32 v[114:115], v[114:115], v[228:229]
	v_pk_mul_f32 v[116:117], v[116:117], v[230:231]
	v_pk_mul_f32 v[118:119], v[118:119], v[232:233]
	v_pk_mul_f32 v[120:121], v[120:121], v[234:235]
	v_min_f32_e32 v114, 0x3f7fffef, v114
	v_min_f32_e32 v115, 0x3f7fffef, v115
	v_min_f32_e32 v116, 0x3f7fffef, v116
	v_min_f32_e32 v117, 0x3f7fffef, v117
	v_min_f32_e32 v118, 0x3f7fffef, v118
	v_min_f32_e32 v119, 0x3f7fffef, v119
	v_min_f32_e32 v120, 0x3f7fffef, v120
	v_min_f32_e32 v121, 0x3f7fffef, v121
	v_pk_add_f32 v[114:115], v[114:115], 1.0 op_sel_hi:[1,0] neg_lo:[1,0] neg_hi:[1,0]
	v_pk_add_f32 v[116:117], v[116:117], 1.0 op_sel_hi:[1,0] neg_lo:[1,0] neg_hi:[1,0]
	v_pk_add_f32 v[118:119], v[118:119], 1.0 op_sel_hi:[1,0] neg_lo:[1,0] neg_hi:[1,0]
	v_pk_add_f32 v[120:121], v[120:121], 1.0 op_sel_hi:[1,0] neg_lo:[1,0] neg_hi:[1,0]
	v_log_f32_e32 v114, v114
	v_log_f32_e32 v115, v115
	v_log_f32_e32 v116, v116
	v_log_f32_e32 v117, v117
	v_log_f32_e32 v118, v118
	v_log_f32_e32 v119, v119
	v_log_f32_e32 v120, v120
	v_log_f32_e32 v121, v121
	v_pk_mul_f32 v[244:245], v[114:115], s[4:5] op_sel_hi:[1,0]
	v_pk_fma_f32 v[244:245], v[114:115], s[4:5], v[244:245] op_sel_hi:[1,0,1] neg_lo:[0,0,1] neg_hi:[0,0,1]
	v_pk_fma_f32 v[244:245], v[114:115], s[10:11], v[244:245] op_sel_hi:[1,0,1]
	v_pk_fma_f32 v[114:115], v[114:115], s[4:5], v[244:245] op_sel_hi:[1,0,1]
	v_pk_mul_f32 v[246:247], v[116:117], s[4:5] op_sel_hi:[1,0]
	v_pk_fma_f32 v[246:247], v[116:117], s[4:5], v[246:247] op_sel_hi:[1,0,1] neg_lo:[0,0,1] neg_hi:[0,0,1]
	v_pk_fma_f32 v[246:247], v[116:117], s[10:11], v[246:247] op_sel_hi:[1,0,1]
	v_pk_fma_f32 v[116:117], v[116:117], s[4:5], v[246:247] op_sel_hi:[1,0,1]
	v_pk_mul_f32 v[244:245], v[118:119], s[4:5] op_sel_hi:[1,0]
	v_pk_fma_f32 v[244:245], v[118:119], s[4:5], v[244:245] op_sel_hi:[1,0,1] neg_lo:[0,0,1] neg_hi:[0,0,1]
	v_pk_fma_f32 v[244:245], v[118:119], s[10:11], v[244:245] op_sel_hi:[1,0,1]
	v_pk_fma_f32 v[118:119], v[118:119], s[4:5], v[244:245] op_sel_hi:[1,0,1]
	v_pk_mul_f32 v[246:247], v[120:121], s[4:5] op_sel_hi:[1,0]
	v_pk_fma_f32 v[246:247], v[120:121], s[4:5], v[246:247] op_sel_hi:[1,0,1] neg_lo:[0,0,1] neg_hi:[0,0,1]
	v_pk_fma_f32 v[246:247], v[120:121], s[10:11], v[246:247] op_sel_hi:[1,0,1]
	v_pk_fma_f32 v[120:121], v[120:121], s[4:5], v[246:247] op_sel_hi:[1,0,1]
	s_mov_b64 s[0:1], 0
	global_store_dwordx4 v[160:161], v[114:117], off nt
	global_store_dwordx4 v[160:161], v[118:121], off offset:16 nt
